# v18 + residual-GEMM epilogues: the 8 per-row-block sum-of-squares atomics of a wave combined into 2 full-wave atomics
# baseline (speedup 1.0000x reference)
; #define ALDS __attribute__((address_space(3)))
; #define ATT_Q_DMA() do { unsigned qo_ = kD - klb; asm volatile("" : "+v"(qo_) :: "memory");     \
;         _Pragma("unroll") for (int c = 0; c < 8; ++c) \
;         __builtin_amdgcn_global_load_lds((const unsigned*)(qb + 1024 * c + (qo_ ^ (unsigned)((c & 3) << 6))), (ALDS unsigned*)(klb + 1024u * c), 16, 0, 0); } while (0)
; __device__ __forceinline__ void na_phase(const bf16* qkv, bf16* out, const float* rpb, ldsp lds, int vcu, int G, int tid_in) {
;     ...
;     if (wave >= 4) return;
;     constexpr size_t PITCH = 128, PLANE = pg8::PLANE; constexpr int NUNITS = 2048;
;     const int per = (NUNITS + G - 1) / G; const int u_lo = vcu * per, u_hi = (u_lo + per < NUNITS) ? u_lo + per : NUNITS;
;     for (int U2 = 2 * u_lo; U2 < 2 * u_hi; ++U2) { const int U = U2 >> 1;
;         int bh_, rq_; if (G == 256) { const int x_ = vcu >> 5, c_ = vcu & 31, i_ = U - u_lo; bh_ = x_ * 4 + (i_ >> 1); rq_ = (i_ & 1) * 32 + c_; } else { bh_ = U >> 6; rq_ = U & 63; }
;         const int b = bh_ >> 4, h = bh_ & 15, row = 4 * rq_ + wave, j = U2 & 1;
;         const int tokb = b * 16384, qc = 32 * j + r32;
;         const char* qb = (const char*)(qkv + (size_t)h * PLANE + (size_t)(tokb + row * 64 + 32 * j) * PITCH);
;         ATT_Q_DMA();
;         const int rs = min(max(row - 4, 0), 248), cs = min(max(qc - 8, 0), 48);
;         const char* kb = (const char*)(qkv + (size_t)(16 + h) * PLANE); const char* vb = (const char*)(qkv + (size_t)(32 + h) * PLANE);
;         const unsigned lane_off = (unsigned)((lane >> 4) * (int)(PITCH * 2) + (lane & 15) * 16);
;         const ALDS float* tbh = tb + h * 465;
.Lhja_entry:
	s_abs_i32 s6, s24
	v_cvt_f32_u32_e32 v1, s6
	s_sub_i32 s9, 0, s6
	s_add_i32 s7, s24, 0x7ff
	s_xor_b32 s8, s7, s24
	v_rcp_iflag_f32_e32 v1, v1
	s_abs_i32 s7, s7
	s_ashr_i32 s8, s8, 31
	v_mul_f32_e32 v1, 0x4f7ffffe, v1
	v_cvt_u32_f32_e32 v1, v1
	s_nop 0
	v_readfirstlane_b32 s10, v1
	s_mul_i32 s9, s9, s10
	s_mul_hi_u32 s9, s10, s9
	s_add_i32 s10, s10, s9
	s_mul_hi_u32 s9, s7, s10
	s_mul_i32 s10, s9, s6
	s_sub_i32 s7, s7, s10
	s_add_i32 s11, s9, 1
	s_sub_i32 s10, s7, s6
	s_cmp_ge_u32 s7, s6
	s_cselect_b32 s9, s11, s9
	s_cselect_b32 s7, s10, s7
	s_add_i32 s10, s9, 1
	s_cmp_ge_u32 s7, s6
	s_cselect_b32 s6, s10, s9
	s_xor_b32 s6, s6, s8
	s_sub_i32 s6, s6, s8
	s_mul_i32 s61, s6, s83
	s_add_i32 s6, s61, s6
	s_min_i32 s6, s6, 0x800
	s_lshl_b32 s62, s61, 1
	s_lshl_b32 s63, s6, 1
	s_sub_i32 s6, s63, 4
	s_cmp_eq_u32 s99, 1
	s_cselect_b32 s62, s6, s62
	s_cselect_b32 s63, s63, s6
	s_cmp_ge_i32 s62, s63
	s_cbranch_scc1 .LBB0_169
	v_bfe_u32 v1, v0, 5, 1
	s_lshl_b32 s64, s81, 8
	v_lshrrev_b32_e32 v12, 3, v0
	v_and_b32_e32 v15, 12, v0
	s_add_i32 s64, s64, 0
	v_bfe_u32 v212, v0, 4, 2
	v_bitop3_b32 v5, v1, v0, 15 bitop3:0x78
	v_lshlrev_b32_e32 v9, 3, v1
	v_bfe_u32 v10, v0, 2, 2
	v_lshlrev_b32_e32 v11, 2, v1
	v_and_b32_e32 v12, 2, v12
	v_bfe_u32 v13, v0, 1, 1
	v_or_b32_e32 v1, v1, v15
	v_and_b32_e32 v2, 63, v0
	v_and_b32_e32 v211, 31, v0
	s_add_i32 s6, s64, 0x2000
	v_and_b32_e32 v3, 15, v0
	v_bitop3_b32 v7, v212, v0, 15 bitop3:0x78
	v_lshlrev_b32_e32 v0, 3, v0
	v_or_b32_e32 v16, v11, v10
	v_bitop3_b32 v1, v12, v1, v13 bitop3:0x36
	v_and_or_b32 v0, v0, 8, s6
	v_lshlrev_b32_e32 v16, 8, v16
	v_lshlrev_b32_e32 v1, 4, v1
	v_add3_u32 v214, v0, v16, v1
	v_or_b32_e32 v1, 8, v11
	v_lshlrev_b32_e32 v4, 8, v211
	v_or_b32_e32 v14, v12, v13
	v_or_b32_e32 v10, v1, v10
	v_lshrrev_b32_e32 v1, 2, v1
	v_lshl_or_b32 v5, v5, 4, v4
	v_bitop3_b32 v1, v1, v14, v15 bitop3:0x36
	v_lshlrev_b32_e32 v3, 4, v3
	v_lshlrev_b32_e32 v10, 8, v10
	v_lshlrev_b32_e32 v1, 4, v1
	v_add_u32_e32 v216, s64, v5
	v_and_b32_e32 v5, 64, v252
	v_lshlrev_b32_e32 v6, 8, v212
	v_lshlrev_b32_e32 v8, 6, v212
	v_add3_u32 v215, v10, v0, v1
	v_or3_b32 v0, v3, v9, v4
	v_add_u32_e32 v5, 64, v5
	v_bitop3_b32 v8, v8, v6, v3 bitop3:0xde
	v_add_u32_e32 v218, s64, v0
	s_cmpk_lg_i32 s24, 0x100
	v_lshlrev_b32_e32 v0, 3, v7
	v_cmp_lt_i32_e32 vcc, v210, v5
	v_lshl_or_b32 v213, v7, 4, v6
	v_add_u32_e32 v217, s6, v8
	s_cselect_b64 s[14:15], -1, 0
	s_ashr_i32 s6, s83, 3
	v_or_b32_e32 v192, v6, v3
	v_mov_b32_e32 v1, 0
	v_lshlrev_b32_e32 v3, 4, v2
	v_xor_b32_e32 v2, 32, v0
	v_xor_b32_e32 v4, 64, v0
	v_xor_b32_e32 v6, 0x60, v0
	v_cndmask_b32_e32 v5, v252, v210, vcc
	s_and_b32 s65, s83, 31
	s_and_b32 s66, s6, -4
	v_mov_b32_e32 v193, v1
	v_xor_b32_e32 v219, 16, v218
	v_xor_b32_e32 v220, 32, v218
	v_xor_b32_e32 v221, 48, v218
	v_xor_b32_e32 v222, 64, v218
	v_xor_b32_e32 v223, 0x50, v218
	v_xor_b32_e32 v224, 0x60, v218
	v_xor_b32_e32 v225, 0x70, v218
	v_xor_b32_e32 v226, 0x80, v218
	v_xor_b32_e32 v227, 0x90, v218
	v_xor_b32_e32 v228, 0xa0, v218
	v_xor_b32_e32 v229, 0xb0, v218
	v_xor_b32_e32 v230, 0xc0, v218
	v_xor_b32_e32 v231, 0xd0, v218
	v_xor_b32_e32 v232, 0xe0, v218
	v_xor_b32_e32 v233, 0xf0, v218
	v_lshlrev_b32_e32 v234, 2, v5
	v_or_b32_e32 v235, 3, v11
	v_sub_u32_e32 v236, v11, v211
	s_bitcmp1_b32 s62, 0
	s_cselect_b64 s[38:39], -1, 0
	s_mov_b64 s[40:41], 0x400
	s_add_i32 s67, s64, 0x400
	s_mov_b64 s[42:43], 0x800
	s_add_i32 s68, s64, 0x800
	s_mov_b64 s[44:45], 0xc00
	s_add_i32 s69, s64, 0xc00
	s_mov_b64 s[46:47], 0x1000
	s_add_i32 s70, s64, 0x1000
	s_mov_b64 s[48:49], 0x1400
	s_add_i32 s71, s64, 0x1400
	s_mov_b64 s[50:51], 0x1800
	s_add_i32 s74, s64, 0x1800
	s_mov_b64 s[52:53], 0x1c00
	s_add_i32 s75, s64, 0x1c00
	s_mov_b64 s[54:55], 0x8000000
	s_mov_b64 s[56:57], 0x10000000
	v_add_u32_e32 v237, s64, v3
	v_lshlrev_b32_e32 v194, 1, v0
	v_lshlrev_b32_e32 v196, 1, v2
	v_lshlrev_b32_e32 v198, 1, v4
	v_lshlrev_b32_e32 v200, 1, v6
	v_mov_b32_e32 v238, 0xf149f2ca
	s_branch .LBB0_156

; #define PG8_LAS __attribute__((address_space(3)))
; __device__ __forceinline__ unsigned cvt_pk_bf16(float lo, float hi) { unsigned r; asm volatile("v_cvt_pk_bf16_f32 %0, %1, %2" : "=v"(r) : "v"(lo), "v"(hi)); return r; }
;     __device__ __forceinline__ void operator()(const f32x4 (&acc)[2][2][4][2], const Unit& u, int wr, int wc, int fr, int fq) const {
;         const int lane = fr + 16 * fq, r = lane >> 2, p = lane & 3; PG8_LAS unsigned char* stg = lds + STG_OFF + (wr * 4 + wc) * STG_WAVE;
; #pragma unroll
;         for (int ai = 0; ai < 2; ++ai)
; #pragma unroll
;             for (int m = 0; m < 4; ++m) {
;                 const int row = u.pm * BM + ai * HALF + wr * 64 + m * 16 + r; float q = 0.f;
; #pragma unroll
;                 for (int bj = 0; bj < 2; ++bj) {
;                     const size_t off = (size_t)row * 2048 + u.pn * BM + wc * 64 + bj * 32 + 8 * p;
;                     f32x4 b0, b1;
;                     if (BASE_F32) { b0 = *(const f32x4*)((const float*)base + off); b1 = *(const f32x4*)((const float*)base + off + 4); }
;                     else { const u32x4 bb = *(const u32x4*)((const bf16_t*)base + off);
;                         b0 = (f32x4){__uint_as_float(bb.x << 16), __uint_as_float(bb.x & 0xffff0000u), __uint_as_float(bb.y << 16), __uint_as_float(bb.y & 0xffff0000u)};
;                         b1 = (f32x4){__uint_as_float(bb.z << 16), __uint_as_float(bb.z & 0xffff0000u), __uint_as_float(bb.w << 16), __uint_as_float(bb.w & 0xffff0000u)}; }
; #pragma unroll
;                     for (int n = 0; n < 2; ++n) *(PG8_LAS f32x4*)(stg + fr * STG_ROW + n * 64 + fq * 16) = acc[ai][bj][m][n];
;                     const f32x4 v0 = *(const PG8_LAS f32x4*)(stg + r * STG_ROW + p * 32) + b0, v1 = *(const PG8_LAS f32x4*)(stg + r * STG_ROW + p * 32 + 16) + b1;
;                     q += ((v0[0] * v0[0] + v0[1] * v0[1]) + (v0[2] * v0[2] + v0[3] * v0[3])) + ((v1[0] * v1[0] + v1[1] * v1[1]) + (v1[2] * v1[2] + v1[3] * v1[3]));
;                     u32x4 w; w.x = cvt_pk_bf16(v0[0], v0[1]); w.y = cvt_pk_bf16(v0[2], v0[3]); w.z = cvt_pk_bf16(v1[0], v1[1]); w.w = cvt_pk_bf16(v1[2], v1[3]);
;                     *(u32x4*)(out + off) = w;
;                 }
;                 q += __shfl_xor(q, 1); q += __shfl_xor(q, 2);
;                 if (p == 0) atomicAdd(ssn + row, (u64)(q * SS_SCALE));
.LBB0_295:
	ds_write_b128 v156, v[124:127]
	ds_write_b128 v156, v[120:123] offset:64
	ds_read_b128 v[120:123], v157
	ds_read_b128 v[124:127], v157 offset:16
	ds_write_b128 v156, v[116:119]
	ds_write_b128 v156, v[112:115] offset:64
	ds_read_b128 v[112:115], v157
	ds_read_b128 v[116:119], v157 offset:16
	s_waitcnt vmcnt(18) lgkmcnt(4)
	v_pk_add_f32 v[120:121], v[160:161], v[120:121]
	v_pk_add_f32 v[122:123], v[162:163], v[122:123]
	v_pk_add_f32 v[124:125], v[164:165], v[124:125]
	v_pk_add_f32 v[126:127], v[166:167], v[126:127]
	v_add_u32_e32 v149, 0x120000, v158
	global_load_dwordx4 v[160:163], v149, s[12:13]
	global_load_dwordx4 v[164:167], v149, s[12:13] offset:16
	v_mul_f32_e32 v244, v121, v121
	v_mul_f32_e32 v245, v123, v123
	v_mul_f32_e32 v246, v125, v125
	v_mul_f32_e32 v247, v127, v127
	v_fmac_f32_e32 v244, v120, v120
	v_fmac_f32_e32 v245, v122, v122
	v_fmac_f32_e32 v246, v124, v124
	v_fmac_f32_e32 v247, v126, v126
	v_cvt_pk_bf16_f32 v120, v120, v121
	v_cvt_pk_bf16_f32 v121, v122, v123
	v_cvt_pk_bf16_f32 v122, v124, v125
	v_cvt_pk_bf16_f32 v123, v126, v127
	v_add_f32_e32 v244, v244, v245
	v_add_f32_e32 v245, v246, v247
	v_add_f32_e32 v124, v244, v245
	global_store_dwordx4 v159, v[120:123], s[38:39]
	ds_write_b128 v156, v[108:111]
	ds_write_b128 v156, v[104:107] offset:64
	ds_read_b128 v[104:107], v157
	ds_read_b128 v[108:111], v157 offset:16
	s_waitcnt vmcnt(19) lgkmcnt(4)
	v_pk_add_f32 v[112:113], v[168:169], v[112:113]
	v_pk_add_f32 v[114:115], v[170:171], v[114:115]
	v_pk_add_f32 v[116:117], v[172:173], v[116:117]
	v_pk_add_f32 v[118:119], v[174:175], v[118:119]
	global_load_dwordx4 v[168:171], v149, s[12:13] offset:128
	global_load_dwordx4 v[172:175], v149, s[12:13] offset:144
	v_mul_f32_e32 v244, v113, v113
	v_mul_f32_e32 v245, v115, v115
	v_mul_f32_e32 v246, v117, v117
	v_mul_f32_e32 v247, v119, v119
	v_fmac_f32_e32 v244, v112, v112
	v_fmac_f32_e32 v245, v114, v114
	v_fmac_f32_e32 v246, v116, v116
	v_fmac_f32_e32 v247, v118, v118
	v_cvt_pk_bf16_f32 v112, v112, v113
	v_cvt_pk_bf16_f32 v113, v114, v115
	v_cvt_pk_bf16_f32 v114, v116, v117
	v_cvt_pk_bf16_f32 v115, v118, v119
	v_add_f32_e32 v244, v244, v245
	v_add_f32_e32 v245, v246, v247
	v_add_f32_e32 v116, v244, v245
	global_store_dwordx4 v159, v[112:115], s[38:39] offset:64
	v_add_f32_e32 v117, v124, v116
	s_nop 1
	v_add_f32_dpp v118, v117, v117 quad_perm:[1,0,3,2] row_mask:0xf bank_mask:0xf
	s_nop 1
	v_add_f32_dpp v119, v118, v118 quad_perm:[2,3,0,1] row_mask:0xf bank_mask:0xf
	v_mul_f32_e32 v126, 0x49800000, v119
	v_trunc_f32_e32 v126, v126
	v_mul_f32_e32 v127, 0x2f800000, v126
	v_floor_f32_e32 v127, v127
	v_fmac_f32_e32 v126, 0xcf800000, v127
	v_cvt_u32_f32_e32 v126, v126
	v_cvt_u32_f32_e32 v127, v127
	ds_write_b128 v156, v[100:103]
	ds_write_b128 v156, v[96:99] offset:64
	ds_read_b128 v[96:99], v157
	ds_read_b128 v[100:103], v157 offset:16
	s_waitcnt vmcnt(20) lgkmcnt(4)
	v_pk_add_f32 v[104:105], v[176:177], v[104:105]
	v_pk_add_f32 v[106:107], v[178:179], v[106:107]
	v_pk_add_f32 v[108:109], v[180:181], v[108:109]
	v_pk_add_f32 v[110:111], v[182:183], v[110:111]
	v_add_u32_e32 v209, 0x140000, v158
	global_load_dwordx4 v[176:179], v209, s[12:13]
	global_load_dwordx4 v[180:183], v209, s[12:13] offset:16
	v_mul_f32_e32 v244, v105, v105
	v_mul_f32_e32 v245, v107, v107
	v_mul_f32_e32 v246, v109, v109
	v_mul_f32_e32 v247, v111, v111
	v_fmac_f32_e32 v244, v104, v104
	v_fmac_f32_e32 v245, v106, v106
	v_fmac_f32_e32 v246, v108, v108
	v_fmac_f32_e32 v247, v110, v110
	v_cvt_pk_bf16_f32 v104, v104, v105
	v_cvt_pk_bf16_f32 v105, v106, v107
	v_cvt_pk_bf16_f32 v106, v108, v109
	v_cvt_pk_bf16_f32 v107, v110, v111
	v_add_f32_e32 v244, v244, v245
	v_add_f32_e32 v245, v246, v247
	v_add_f32_e32 v108, v244, v245
	v_add_u32_e32 v147, 0x10000, v159
	global_store_dwordx4 v147, v[104:107], s[38:39]
	ds_write_b128 v156, v[92:95]
	ds_write_b128 v156, v[88:91] offset:64
	ds_read_b128 v[88:91], v157
	ds_read_b128 v[92:95], v157 offset:16
	s_waitcnt vmcnt(21) lgkmcnt(4)
	v_pk_add_f32 v[96:97], v[184:185], v[96:97]
	v_pk_add_f32 v[98:99], v[186:187], v[98:99]
	v_pk_add_f32 v[100:101], v[188:189], v[100:101]
	v_pk_add_f32 v[102:103], v[190:191], v[102:103]
	global_load_dwordx4 v[184:187], v209, s[12:13] offset:128
	global_load_dwordx4 v[188:191], v209, s[12:13] offset:144
	v_mul_f32_e32 v244, v97, v97
	v_mul_f32_e32 v245, v99, v99
	v_mul_f32_e32 v246, v101, v101
	v_mul_f32_e32 v247, v103, v103
	v_fmac_f32_e32 v244, v96, v96
	v_fmac_f32_e32 v245, v98, v98
	v_fmac_f32_e32 v246, v100, v100
	v_fmac_f32_e32 v247, v102, v102
	v_cvt_pk_bf16_f32 v96, v96, v97
	v_cvt_pk_bf16_f32 v97, v98, v99
	v_cvt_pk_bf16_f32 v98, v100, v101
	v_cvt_pk_bf16_f32 v99, v102, v103
	v_add_f32_e32 v244, v244, v245
	v_add_f32_e32 v245, v246, v247
	v_add_f32_e32 v100, v244, v245
	global_store_dwordx4 v147, v[96:99], s[38:39] offset:64
	v_add_f32_e32 v101, v108, v100
	s_nop 1
	v_add_f32_dpp v102, v101, v101 quad_perm:[1,0,3,2] row_mask:0xf bank_mask:0xf
	s_nop 1
	v_add_f32_dpp v103, v102, v102 quad_perm:[2,3,0,1] row_mask:0xf bank_mask:0xf
	v_mul_f32_e32 v110, 0x49800000, v103
	v_trunc_f32_e32 v110, v110
	v_mul_f32_e32 v111, 0x2f800000, v110
	v_floor_f32_e32 v111, v111
	v_fmac_f32_e32 v110, 0xcf800000, v111
	v_cvt_u32_f32_e32 v110, v110
	v_cvt_u32_f32_e32 v111, v111
	ds_write_b128 v156, v[84:87]
	ds_write_b128 v156, v[80:83] offset:64
	ds_read_b128 v[80:83], v157
	ds_read_b128 v[84:87], v157 offset:16
	s_waitcnt vmcnt(22) lgkmcnt(4)
; #define PG8_LAS __attribute__((address_space(3)))
; __device__ __forceinline__ unsigned cvt_pk_bf16(float lo, float hi) { unsigned r; asm volatile("v_cvt_pk_bf16_f32 %0, %1, %2" : "=v"(r) : "v"(lo), "v"(hi)); return r; }
;     __device__ __forceinline__ void operator()(const f32x4 (&acc)[2][2][4][2], const Unit& u, int wr, int wc, int fr, int fq) const {
;         const int lane = fr + 16 * fq, r = lane >> 2, p = lane & 3; PG8_LAS unsigned char* stg = lds + STG_OFF + (wr * 4 + wc) * STG_WAVE;
; #pragma unroll
;         for (int ai = 0; ai < 2; ++ai)
; #pragma unroll
;             for (int m = 0; m < 4; ++m) {
;                 const int row = u.pm * BM + ai * HALF + wr * 64 + m * 16 + r; float q = 0.f;
; #pragma unroll
;                 for (int bj = 0; bj < 2; ++bj) {
;                     const size_t off = (size_t)row * 2048 + u.pn * BM + wc * 64 + bj * 32 + 8 * p;
;                     f32x4 b0, b1;
;                     if (BASE_F32) { b0 = *(const f32x4*)((const float*)base + off); b1 = *(const f32x4*)((const float*)base + off + 4); }
;                     else { const u32x4 bb = *(const u32x4*)((const bf16_t*)base + off);
;                         b0 = (f32x4){__uint_as_float(bb.x << 16), __uint_as_float(bb.x & 0xffff0000u), __uint_as_float(bb.y << 16), __uint_as_float(bb.y & 0xffff0000u)};
;                         b1 = (f32x4){__uint_as_float(bb.z << 16), __uint_as_float(bb.z & 0xffff0000u), __uint_as_float(bb.w << 16), __uint_as_float(bb.w & 0xffff0000u)}; }
; #pragma unroll
;                     for (int n = 0; n < 2; ++n) *(PG8_LAS f32x4*)(stg + fr * STG_ROW + n * 64 + fq * 16) = acc[ai][bj][m][n];
;                     const f32x4 v0 = *(const PG8_LAS f32x4*)(stg + r * STG_ROW + p * 32) + b0, v1 = *(const PG8_LAS f32x4*)(stg + r * STG_ROW + p * 32 + 16) + b1;
;                     q += ((v0[0] * v0[0] + v0[1] * v0[1]) + (v0[2] * v0[2] + v0[3] * v0[3])) + ((v1[0] * v1[0] + v1[1] * v1[1]) + (v1[2] * v1[2] + v1[3] * v1[3]));
;                     u32x4 w; w.x = cvt_pk_bf16(v0[0], v0[1]); w.y = cvt_pk_bf16(v0[2], v0[3]); w.z = cvt_pk_bf16(v1[0], v1[1]); w.w = cvt_pk_bf16(v1[2], v1[3]);
;                     *(u32x4*)(out + off) = w;
;                 }
;                 q += __shfl_xor(q, 1); q += __shfl_xor(q, 2);
;                 if (p == 0) atomicAdd(ssn + row, (u64)(q * SS_SCALE));
	v_pk_add_f32 v[88:89], v[192:193], v[88:89]
	v_pk_add_f32 v[90:91], v[194:195], v[90:91]
	v_pk_add_f32 v[92:93], v[196:197], v[92:93]
	v_pk_add_f32 v[94:95], v[198:199], v[94:95]
	v_add_u32_e32 v149, 0x160000, v158
	global_load_dwordx4 v[192:195], v149, s[12:13]
	global_load_dwordx4 v[196:199], v149, s[12:13] offset:16
	v_mul_f32_e32 v244, v89, v89
	v_mul_f32_e32 v245, v91, v91
	v_mul_f32_e32 v246, v93, v93
	v_mul_f32_e32 v247, v95, v95
	v_fmac_f32_e32 v244, v88, v88
	v_fmac_f32_e32 v245, v90, v90
	v_fmac_f32_e32 v246, v92, v92
	v_fmac_f32_e32 v247, v94, v94
	v_cvt_pk_bf16_f32 v88, v88, v89
	v_cvt_pk_bf16_f32 v89, v90, v91
	v_cvt_pk_bf16_f32 v90, v92, v93
	v_cvt_pk_bf16_f32 v91, v94, v95
	v_add_f32_e32 v244, v244, v245
	v_add_f32_e32 v245, v246, v247
	v_add_f32_e32 v92, v244, v245
	v_add_u32_e32 v146, 0x20000, v159
	global_store_dwordx4 v146, v[88:91], s[38:39]
	ds_write_b128 v156, v[76:79]
	ds_write_b128 v156, v[72:75] offset:64
	ds_read_b128 v[72:75], v157
	ds_read_b128 v[76:79], v157 offset:16
	s_waitcnt vmcnt(23) lgkmcnt(4)
	v_pk_add_f32 v[80:81], v[200:201], v[80:81]
	v_pk_add_f32 v[82:83], v[202:203], v[82:83]
	v_pk_add_f32 v[84:85], v[204:205], v[84:85]
	v_pk_add_f32 v[86:87], v[206:207], v[86:87]
	global_load_dwordx4 v[200:203], v149, s[12:13] offset:128
	global_load_dwordx4 v[204:207], v149, s[12:13] offset:144
	v_mul_f32_e32 v244, v81, v81
	v_mul_f32_e32 v245, v83, v83
	v_mul_f32_e32 v246, v85, v85
	v_mul_f32_e32 v247, v87, v87
	v_fmac_f32_e32 v244, v80, v80
	v_fmac_f32_e32 v245, v82, v82
	v_fmac_f32_e32 v246, v84, v84
	v_fmac_f32_e32 v247, v86, v86
	v_cvt_pk_bf16_f32 v80, v80, v81
	v_cvt_pk_bf16_f32 v81, v82, v83
	v_cvt_pk_bf16_f32 v82, v84, v85
	v_cvt_pk_bf16_f32 v83, v86, v87
	v_add_f32_e32 v244, v244, v245
	v_add_f32_e32 v245, v246, v247
	v_add_f32_e32 v84, v244, v245
	global_store_dwordx4 v146, v[80:83], s[38:39] offset:64
	v_add_f32_e32 v85, v92, v84
	s_nop 1
	v_add_f32_dpp v86, v85, v85 quad_perm:[1,0,3,2] row_mask:0xf bank_mask:0xf
	s_nop 1
	v_add_f32_dpp v87, v86, v86 quad_perm:[2,3,0,1] row_mask:0xf bank_mask:0xf
	v_mul_f32_e32 v94, 0x49800000, v87
	v_trunc_f32_e32 v94, v94
	v_mul_f32_e32 v95, 0x2f800000, v94
	v_floor_f32_e32 v95, v95
	v_fmac_f32_e32 v94, 0xcf800000, v95
	v_cvt_u32_f32_e32 v94, v94
	v_cvt_u32_f32_e32 v95, v95
	ds_write_b128 v156, v[68:71]
	ds_write_b128 v156, v[64:67] offset:64
	ds_read_b128 v[64:67], v157
	ds_read_b128 v[68:71], v157 offset:16
	s_waitcnt vmcnt(24) lgkmcnt(4)
	v_pk_add_f32 v[72:73], v[212:213], v[72:73]
	v_pk_add_f32 v[74:75], v[214:215], v[74:75]
	v_pk_add_f32 v[76:77], v[216:217], v[76:77]
	v_pk_add_f32 v[78:79], v[218:219], v[78:79]
	v_mul_f32_e32 v244, v73, v73
	v_mul_f32_e32 v245, v75, v75
	v_mul_f32_e32 v246, v77, v77
	v_mul_f32_e32 v247, v79, v79
	v_fmac_f32_e32 v244, v72, v72
	v_fmac_f32_e32 v245, v74, v74
	v_fmac_f32_e32 v246, v76, v76
	v_fmac_f32_e32 v247, v78, v78
	v_cvt_pk_bf16_f32 v72, v72, v73
	v_cvt_pk_bf16_f32 v73, v74, v75
	v_cvt_pk_bf16_f32 v74, v76, v77
	v_cvt_pk_bf16_f32 v75, v78, v79
	v_add_f32_e32 v244, v244, v245
	v_add_f32_e32 v245, v246, v247
	v_add_f32_e32 v76, v244, v245
	v_add_u32_e32 v147, 0x30000, v159
	global_store_dwordx4 v147, v[72:75], s[38:39]
	ds_write_b128 v156, v[60:63]
	ds_write_b128 v156, v[56:59] offset:64
	ds_read_b128 v[56:59], v157
	ds_read_b128 v[60:63], v157 offset:16
	s_waitcnt vmcnt(23) lgkmcnt(4)
	v_pk_add_f32 v[64:65], v[220:221], v[64:65]
	v_pk_add_f32 v[66:67], v[222:223], v[66:67]
	v_pk_add_f32 v[68:69], v[224:225], v[68:69]
	v_pk_add_f32 v[70:71], v[226:227], v[70:71]
	v_mul_f32_e32 v244, v65, v65
	v_mul_f32_e32 v245, v67, v67
	v_mul_f32_e32 v246, v69, v69
	v_mul_f32_e32 v247, v71, v71
	v_fmac_f32_e32 v244, v64, v64
	v_fmac_f32_e32 v245, v66, v66
	v_fmac_f32_e32 v246, v68, v68
	v_fmac_f32_e32 v247, v70, v70
	v_cvt_pk_bf16_f32 v64, v64, v65
	v_cvt_pk_bf16_f32 v65, v66, v67
	v_cvt_pk_bf16_f32 v66, v68, v69
	v_cvt_pk_bf16_f32 v67, v70, v71
	v_add_f32_e32 v244, v244, v245
	v_add_f32_e32 v245, v246, v247
	v_add_f32_e32 v68, v244, v245
	global_store_dwordx4 v147, v[64:67], s[38:39] offset:64
	v_add_f32_e32 v69, v76, v68
	s_nop 1
	v_add_f32_dpp v70, v69, v69 quad_perm:[1,0,3,2] row_mask:0xf bank_mask:0xf
	s_nop 1
	v_add_f32_dpp v71, v70, v70 quad_perm:[2,3,0,1] row_mask:0xf bank_mask:0xf
	v_mul_f32_e32 v78, 0x49800000, v71
	v_trunc_f32_e32 v78, v78
	v_mul_f32_e32 v79, 0x2f800000, v78
	v_floor_f32_e32 v79, v79
	v_fmac_f32_e32 v78, 0xcf800000, v79
	v_cvt_u32_f32_e32 v78, v78
	v_cvt_u32_f32_e32 v79, v79
	ds_write_b128 v156, v[52:55]
	ds_write_b128 v156, v[48:51] offset:64
	ds_read_b128 v[48:51], v157
	ds_read_b128 v[52:55], v157 offset:16
	s_waitcnt vmcnt(22) lgkmcnt(4)
	v_pk_add_f32 v[56:57], v[228:229], v[56:57]
	v_pk_add_f32 v[58:59], v[230:231], v[58:59]
	v_pk_add_f32 v[60:61], v[232:233], v[60:61]
	v_pk_add_f32 v[62:63], v[234:235], v[62:63]
	v_mul_f32_e32 v244, v57, v57
	v_mul_f32_e32 v245, v59, v59
	v_mul_f32_e32 v246, v61, v61
	v_mul_f32_e32 v247, v63, v63
	v_fmac_f32_e32 v244, v56, v56
	v_fmac_f32_e32 v245, v58, v58
	v_fmac_f32_e32 v246, v60, v60
	v_fmac_f32_e32 v247, v62, v62
	v_cvt_pk_bf16_f32 v56, v56, v57
	v_cvt_pk_bf16_f32 v57, v58, v59
	v_cvt_pk_bf16_f32 v58, v60, v61
	v_cvt_pk_bf16_f32 v59, v62, v63
	v_add_f32_e32 v244, v244, v245
	v_add_f32_e32 v245, v246, v247
	v_add_f32_e32 v60, v244, v245
	v_add_u32_e32 v146, 0x80000, v159
	global_store_dwordx4 v146, v[56:59], s[38:39]
	ds_write_b128 v156, v[44:47]
	ds_write_b128 v156, v[40:43] offset:64
	ds_read_b128 v[40:43], v157
	ds_read_b128 v[44:47], v157 offset:16
	s_waitcnt vmcnt(21) lgkmcnt(4)
; #define PG8_LAS __attribute__((address_space(3)))
; __device__ __forceinline__ unsigned cvt_pk_bf16(float lo, float hi) { unsigned r; asm volatile("v_cvt_pk_bf16_f32 %0, %1, %2" : "=v"(r) : "v"(lo), "v"(hi)); return r; }
;     __device__ __forceinline__ void operator()(const f32x4 (&acc)[2][2][4][2], const Unit& u, int wr, int wc, int fr, int fq) const {
;         const int lane = fr + 16 * fq, r = lane >> 2, p = lane & 3; PG8_LAS unsigned char* stg = lds + STG_OFF + (wr * 4 + wc) * STG_WAVE;
; #pragma unroll
;         for (int ai = 0; ai < 2; ++ai)
; #pragma unroll
;             for (int m = 0; m < 4; ++m) {
;                 const int row = u.pm * BM + ai * HALF + wr * 64 + m * 16 + r; float q = 0.f;
; #pragma unroll
;                 for (int bj = 0; bj < 2; ++bj) {
;                     const size_t off = (size_t)row * 2048 + u.pn * BM + wc * 64 + bj * 32 + 8 * p;
;                     f32x4 b0, b1;
;                     if (BASE_F32) { b0 = *(const f32x4*)((const float*)base + off); b1 = *(const f32x4*)((const float*)base + off + 4); }
;                     else { const u32x4 bb = *(const u32x4*)((const bf16_t*)base + off);
;                         b0 = (f32x4){__uint_as_float(bb.x << 16), __uint_as_float(bb.x & 0xffff0000u), __uint_as_float(bb.y << 16), __uint_as_float(bb.y & 0xffff0000u)};
;                         b1 = (f32x4){__uint_as_float(bb.z << 16), __uint_as_float(bb.z & 0xffff0000u), __uint_as_float(bb.w << 16), __uint_as_float(bb.w & 0xffff0000u)}; }
; #pragma unroll
;                     for (int n = 0; n < 2; ++n) *(PG8_LAS f32x4*)(stg + fr * STG_ROW + n * 64 + fq * 16) = acc[ai][bj][m][n];
;                     const f32x4 v0 = *(const PG8_LAS f32x4*)(stg + r * STG_ROW + p * 32) + b0, v1 = *(const PG8_LAS f32x4*)(stg + r * STG_ROW + p * 32 + 16) + b1;
;                     q += ((v0[0] * v0[0] + v0[1] * v0[1]) + (v0[2] * v0[2] + v0[3] * v0[3])) + ((v1[0] * v1[0] + v1[1] * v1[1]) + (v1[2] * v1[2] + v1[3] * v1[3]));
;                     u32x4 w; w.x = cvt_pk_bf16(v0[0], v0[1]); w.y = cvt_pk_bf16(v0[2], v0[3]); w.z = cvt_pk_bf16(v1[0], v1[1]); w.w = cvt_pk_bf16(v1[2], v1[3]);
;                     *(u32x4*)(out + off) = w;
;                 }
;                 q += __shfl_xor(q, 1); q += __shfl_xor(q, 2);
;                 if (p == 0) atomicAdd(ssn + row, (u64)(q * SS_SCALE));
	v_pk_add_f32 v[48:49], v[236:237], v[48:49]
	v_pk_add_f32 v[50:51], v[238:239], v[50:51]
	v_pk_add_f32 v[52:53], v[240:241], v[52:53]
	v_pk_add_f32 v[54:55], v[242:243], v[54:55]
	v_mul_f32_e32 v244, v49, v49
	v_mul_f32_e32 v245, v51, v51
	v_mul_f32_e32 v246, v53, v53
	v_mul_f32_e32 v247, v55, v55
	v_fmac_f32_e32 v244, v48, v48
	v_fmac_f32_e32 v245, v50, v50
	v_fmac_f32_e32 v246, v52, v52
	v_fmac_f32_e32 v247, v54, v54
	v_cvt_pk_bf16_f32 v48, v48, v49
	v_cvt_pk_bf16_f32 v49, v50, v51
	v_cvt_pk_bf16_f32 v50, v52, v53
	v_cvt_pk_bf16_f32 v51, v54, v55
	v_add_f32_e32 v244, v244, v245
	v_add_f32_e32 v245, v246, v247
	v_add_f32_e32 v52, v244, v245
	global_store_dwordx4 v146, v[48:51], s[38:39] offset:64
	v_add_f32_e32 v53, v60, v52
	s_nop 1
	v_add_f32_dpp v54, v53, v53 quad_perm:[1,0,3,2] row_mask:0xf bank_mask:0xf
	s_nop 1
	v_add_f32_dpp v55, v54, v54 quad_perm:[2,3,0,1] row_mask:0xf bank_mask:0xf
	v_mul_f32_e32 v62, 0x49800000, v55
	v_trunc_f32_e32 v62, v62
	v_mul_f32_e32 v63, 0x2f800000, v62
	v_floor_f32_e32 v63, v63
	v_fmac_f32_e32 v62, 0xcf800000, v63
	v_cvt_u32_f32_e32 v62, v62
	v_cvt_u32_f32_e32 v63, v63
	ds_write_b128 v156, v[36:39]
	ds_write_b128 v156, v[32:35] offset:64
	ds_read_b128 v[32:35], v157
	ds_read_b128 v[36:39], v157 offset:16
	s_waitcnt vmcnt(20) lgkmcnt(4)
	v_pk_add_f32 v[40:41], v[160:161], v[40:41]
	v_pk_add_f32 v[42:43], v[162:163], v[42:43]
	v_pk_add_f32 v[44:45], v[164:165], v[44:45]
	v_pk_add_f32 v[46:47], v[166:167], v[46:47]
	v_mul_f32_e32 v244, v41, v41
	v_mul_f32_e32 v245, v43, v43
	v_mul_f32_e32 v246, v45, v45
	v_mul_f32_e32 v247, v47, v47
	v_fmac_f32_e32 v244, v40, v40
	v_fmac_f32_e32 v245, v42, v42
	v_fmac_f32_e32 v246, v44, v44
	v_fmac_f32_e32 v247, v46, v46
	v_cvt_pk_bf16_f32 v40, v40, v41
	v_cvt_pk_bf16_f32 v41, v42, v43
	v_cvt_pk_bf16_f32 v42, v44, v45
	v_cvt_pk_bf16_f32 v43, v46, v47
	v_add_f32_e32 v244, v244, v245
	v_add_f32_e32 v245, v246, v247
	v_add_f32_e32 v44, v244, v245
	v_add_u32_e32 v147, 0x90000, v159
	global_store_dwordx4 v147, v[40:43], s[38:39]
	ds_write_b128 v156, v[28:31]
	ds_write_b128 v156, v[24:27] offset:64
	ds_read_b128 v[24:27], v157
	ds_read_b128 v[28:31], v157 offset:16
	s_waitcnt vmcnt(18) lgkmcnt(4)
	v_pk_add_f32 v[32:33], v[168:169], v[32:33]
	v_pk_add_f32 v[34:35], v[170:171], v[34:35]
	v_pk_add_f32 v[36:37], v[172:173], v[36:37]
	v_pk_add_f32 v[38:39], v[174:175], v[38:39]
	v_mul_f32_e32 v244, v33, v33
	v_mul_f32_e32 v245, v35, v35
	v_mul_f32_e32 v246, v37, v37
	v_mul_f32_e32 v247, v39, v39
	v_fmac_f32_e32 v244, v32, v32
	v_fmac_f32_e32 v245, v34, v34
	v_fmac_f32_e32 v246, v36, v36
	v_fmac_f32_e32 v247, v38, v38
	v_cvt_pk_bf16_f32 v32, v32, v33
	v_cvt_pk_bf16_f32 v33, v34, v35
	v_cvt_pk_bf16_f32 v34, v36, v37
	v_cvt_pk_bf16_f32 v35, v38, v39
	v_add_f32_e32 v244, v244, v245
	v_add_f32_e32 v245, v246, v247
	v_add_f32_e32 v36, v244, v245
	global_store_dwordx4 v147, v[32:35], s[38:39] offset:64
	v_add_f32_e32 v37, v44, v36
	s_nop 1
	v_add_f32_dpp v38, v37, v37 quad_perm:[1,0,3,2] row_mask:0xf bank_mask:0xf
	s_nop 1
	v_add_f32_dpp v39, v38, v38 quad_perm:[2,3,0,1] row_mask:0xf bank_mask:0xf
	v_mul_f32_e32 v46, 0x49800000, v39
	v_trunc_f32_e32 v46, v46
	v_mul_f32_e32 v47, 0x2f800000, v46
	v_floor_f32_e32 v47, v47
	v_fmac_f32_e32 v46, 0xcf800000, v47
	v_cvt_u32_f32_e32 v46, v46
	v_cvt_u32_f32_e32 v47, v47
	ds_write_b128 v156, v[20:23]
	ds_write_b128 v156, v[16:19] offset:64
	ds_read_b128 v[16:19], v157
	ds_read_b128 v[20:23], v157 offset:16
	s_waitcnt vmcnt(16) lgkmcnt(4)
	v_pk_add_f32 v[24:25], v[176:177], v[24:25]
	v_pk_add_f32 v[26:27], v[178:179], v[26:27]
	v_pk_add_f32 v[28:29], v[180:181], v[28:29]
	v_pk_add_f32 v[30:31], v[182:183], v[30:31]
	v_mul_f32_e32 v244, v25, v25
	v_mul_f32_e32 v245, v27, v27
	v_mul_f32_e32 v246, v29, v29
	v_mul_f32_e32 v247, v31, v31
	v_fmac_f32_e32 v244, v24, v24
	v_fmac_f32_e32 v245, v26, v26
	v_fmac_f32_e32 v246, v28, v28
	v_fmac_f32_e32 v247, v30, v30
	v_cvt_pk_bf16_f32 v24, v24, v25
	v_cvt_pk_bf16_f32 v25, v26, v27
	v_cvt_pk_bf16_f32 v26, v28, v29
	v_cvt_pk_bf16_f32 v27, v30, v31
	v_add_f32_e32 v244, v244, v245
	v_add_f32_e32 v245, v246, v247
	v_add_f32_e32 v28, v244, v245
	v_add_u32_e32 v146, 0xa0000, v159
	global_store_dwordx4 v146, v[24:27], s[38:39]
	ds_write_b128 v156, v[12:15]
	ds_write_b128 v156, v[8:11] offset:64
	ds_read_b128 v[8:11], v157
	ds_read_b128 v[12:15], v157 offset:16
	s_waitcnt vmcnt(14) lgkmcnt(4)
; #define PG8_LAS __attribute__((address_space(3)))
; __device__ __forceinline__ unsigned cvt_pk_bf16(float lo, float hi) { unsigned r; asm volatile("v_cvt_pk_bf16_f32 %0, %1, %2" : "=v"(r) : "v"(lo), "v"(hi)); return r; }
;     __device__ __forceinline__ void operator()(const f32x4 (&acc)[2][2][4][2], const Unit& u, int wr, int wc, int fr, int fq) const {
;         const int lane = fr + 16 * fq, r = lane >> 2, p = lane & 3; PG8_LAS unsigned char* stg = lds + STG_OFF + (wr * 4 + wc) * STG_WAVE;
; #pragma unroll
;         for (int ai = 0; ai < 2; ++ai)
; #pragma unroll
;             for (int m = 0; m < 4; ++m) {
;                 const int row = u.pm * BM + ai * HALF + wr * 64 + m * 16 + r; float q = 0.f;
; #pragma unroll
;                 for (int bj = 0; bj < 2; ++bj) {
;                     const size_t off = (size_t)row * 2048 + u.pn * BM + wc * 64 + bj * 32 + 8 * p;
;                     f32x4 b0, b1;
;                     if (BASE_F32) { b0 = *(const f32x4*)((const float*)base + off); b1 = *(const f32x4*)((const float*)base + off + 4); }
;                     else { const u32x4 bb = *(const u32x4*)((const bf16_t*)base + off);
;                         b0 = (f32x4){__uint_as_float(bb.x << 16), __uint_as_float(bb.x & 0xffff0000u), __uint_as_float(bb.y << 16), __uint_as_float(bb.y & 0xffff0000u)};
;                         b1 = (f32x4){__uint_as_float(bb.z << 16), __uint_as_float(bb.z & 0xffff0000u), __uint_as_float(bb.w << 16), __uint_as_float(bb.w & 0xffff0000u)}; }
; #pragma unroll
;                     for (int n = 0; n < 2; ++n) *(PG8_LAS f32x4*)(stg + fr * STG_ROW + n * 64 + fq * 16) = acc[ai][bj][m][n];
;                     const f32x4 v0 = *(const PG8_LAS f32x4*)(stg + r * STG_ROW + p * 32) + b0, v1 = *(const PG8_LAS f32x4*)(stg + r * STG_ROW + p * 32 + 16) + b1;
;                     q += ((v0[0] * v0[0] + v0[1] * v0[1]) + (v0[2] * v0[2] + v0[3] * v0[3])) + ((v1[0] * v1[0] + v1[1] * v1[1]) + (v1[2] * v1[2] + v1[3] * v1[3]));
;                     u32x4 w; w.x = cvt_pk_bf16(v0[0], v0[1]); w.y = cvt_pk_bf16(v0[2], v0[3]); w.z = cvt_pk_bf16(v1[0], v1[1]); w.w = cvt_pk_bf16(v1[2], v1[3]);
;                     *(u32x4*)(out + off) = w;
;                 }
;                 q += __shfl_xor(q, 1); q += __shfl_xor(q, 2);
;                 if (p == 0) atomicAdd(ssn + row, (u64)(q * SS_SCALE));
	v_pk_add_f32 v[16:17], v[184:185], v[16:17]
	v_pk_add_f32 v[18:19], v[186:187], v[18:19]
	v_pk_add_f32 v[20:21], v[188:189], v[20:21]
	v_pk_add_f32 v[22:23], v[190:191], v[22:23]
	v_mul_f32_e32 v244, v17, v17
	v_mul_f32_e32 v245, v19, v19
	v_mul_f32_e32 v246, v21, v21
	v_mul_f32_e32 v247, v23, v23
	v_fmac_f32_e32 v244, v16, v16
	v_fmac_f32_e32 v245, v18, v18
	v_fmac_f32_e32 v246, v20, v20
	v_fmac_f32_e32 v247, v22, v22
	v_cvt_pk_bf16_f32 v16, v16, v17
	v_cvt_pk_bf16_f32 v17, v18, v19
	v_cvt_pk_bf16_f32 v18, v20, v21
	v_cvt_pk_bf16_f32 v19, v22, v23
	v_add_f32_e32 v244, v244, v245
	v_add_f32_e32 v245, v246, v247
	v_add_f32_e32 v20, v244, v245
	global_store_dwordx4 v146, v[16:19], s[38:39] offset:64
	v_add_f32_e32 v21, v28, v20
	s_nop 1
	v_add_f32_dpp v22, v21, v21 quad_perm:[1,0,3,2] row_mask:0xf bank_mask:0xf
	s_nop 1
	v_add_f32_dpp v23, v22, v22 quad_perm:[2,3,0,1] row_mask:0xf bank_mask:0xf
	v_mul_f32_e32 v30, 0x49800000, v23
	v_trunc_f32_e32 v30, v30
	v_mul_f32_e32 v31, 0x2f800000, v30
	v_floor_f32_e32 v31, v31
	v_fmac_f32_e32 v30, 0xcf800000, v31
	v_cvt_u32_f32_e32 v30, v30
	v_cvt_u32_f32_e32 v31, v31
	ds_write_b128 v156, v[4:7]
	ds_write_b128 v156, v[0:3] offset:64
	ds_read_b128 v[0:3], v157
	ds_read_b128 v[4:7], v157 offset:16
	s_waitcnt vmcnt(12) lgkmcnt(4)
	v_pk_add_f32 v[8:9], v[192:193], v[8:9]
	v_pk_add_f32 v[10:11], v[194:195], v[10:11]
	v_pk_add_f32 v[12:13], v[196:197], v[12:13]
	v_pk_add_f32 v[14:15], v[198:199], v[14:15]
	v_mul_f32_e32 v244, v9, v9
	v_mul_f32_e32 v245, v11, v11
	v_mul_f32_e32 v246, v13, v13
	v_mul_f32_e32 v247, v15, v15
	v_fmac_f32_e32 v244, v8, v8
	v_fmac_f32_e32 v245, v10, v10
	v_fmac_f32_e32 v246, v12, v12
	v_fmac_f32_e32 v247, v14, v14
	v_cvt_pk_bf16_f32 v8, v8, v9
	v_cvt_pk_bf16_f32 v9, v10, v11
	v_cvt_pk_bf16_f32 v10, v12, v13
	v_cvt_pk_bf16_f32 v11, v14, v15
	v_add_f32_e32 v244, v244, v245
	v_add_f32_e32 v245, v246, v247
	v_add_f32_e32 v12, v244, v245
	v_add_u32_e32 v147, 0xb0000, v159
	global_store_dwordx4 v147, v[8:11], s[38:39]
	s_waitcnt vmcnt(10) lgkmcnt(0)
	v_pk_add_f32 v[0:1], v[200:201], v[0:1]
	v_pk_add_f32 v[2:3], v[202:203], v[2:3]
	v_pk_add_f32 v[4:5], v[204:205], v[4:5]
	v_pk_add_f32 v[6:7], v[206:207], v[6:7]
	v_mul_f32_e32 v244, v1, v1
	v_mul_f32_e32 v245, v3, v3
	v_mul_f32_e32 v246, v5, v5
	v_mul_f32_e32 v247, v7, v7
	v_fmac_f32_e32 v244, v0, v0
	v_fmac_f32_e32 v245, v2, v2
	v_fmac_f32_e32 v246, v4, v4
	v_fmac_f32_e32 v247, v6, v6
	v_cvt_pk_bf16_f32 v0, v0, v1
	v_cvt_pk_bf16_f32 v1, v2, v3
	v_cvt_pk_bf16_f32 v2, v4, v5
	v_cvt_pk_bf16_f32 v3, v6, v7
	v_add_f32_e32 v244, v244, v245
	v_add_f32_e32 v245, v246, v247
	v_add_f32_e32 v4, v244, v245
	global_store_dwordx4 v147, v[0:3], s[38:39] offset:64
	v_add_f32_e32 v5, v12, v4
	s_nop 1
	v_add_f32_dpp v6, v5, v5 quad_perm:[1,0,3,2] row_mask:0xf bank_mask:0xf
	s_nop 1
	v_add_f32_dpp v7, v6, v6 quad_perm:[2,3,0,1] row_mask:0xf bank_mask:0xf
	v_mul_f32_e32 v14, 0x49800000, v7
	v_trunc_f32_e32 v14, v14
	v_mul_f32_e32 v15, 0x2f800000, v14
	v_floor_f32_e32 v15, v15
	v_fmac_f32_e32 v14, 0xcf800000, v15
	v_cvt_u32_f32_e32 v14, v14
	v_cvt_u32_f32_e32 v15, v15
	v_and_b32_e32 v244, 3, v252
	v_lshl_add_u32 v245, v244, 7, v208
	v_cmp_eq_u32_e64 s[100:101], 1, v244
	v_cndmask_b32_e64 v126, v126, v110, s[100:101]
	v_cndmask_b32_e64 v127, v127, v111, s[100:101]
	v_cmp_eq_u32_e64 s[100:101], 2, v244
	v_cndmask_b32_e64 v126, v126, v94, s[100:101]
	v_cndmask_b32_e64 v127, v127, v95, s[100:101]
	v_cmp_eq_u32_e64 s[100:101], 3, v244
	v_cndmask_b32_e64 v126, v126, v78, s[100:101]
	v_cndmask_b32_e64 v127, v127, v79, s[100:101]
	global_atomic_add_x2 v245, v[126:127], s[14:15]
	v_cmp_eq_u32_e64 s[100:101], 1, v244
	v_cndmask_b32_e64 v62, v62, v46, s[100:101]
	v_cndmask_b32_e64 v63, v63, v47, s[100:101]
	v_cmp_eq_u32_e64 s[100:101], 2, v244
	v_cndmask_b32_e64 v62, v62, v30, s[100:101]
	v_cndmask_b32_e64 v63, v63, v31, s[100:101]
	v_cmp_eq_u32_e64 s[100:101], 3, v244
	v_cndmask_b32_e64 v62, v62, v14, s[100:101]
	v_cndmask_b32_e64 v63, v63, v15, s[100:101]
	global_atomic_add_x2 v245, v[62:63], s[14:15] offset:1024
	s_andn2_b64 vcc, exec, s[10:11]
	s_mov_b64 s[10:11], -1
	s_cbranch_vccnz .LBB0_284
	s_andn2_b64 vcc, exec, s[40:41]
	s_cbranch_vccnz .LBB0_283
	s_mov_b32 s98, 1
	s_branch .LBB0_283

; #define PG8_LAS __attribute__((address_space(3)))
; __device__ __forceinline__ unsigned cvt_pk_bf16(float lo, float hi) { unsigned r; asm volatile("v_cvt_pk_bf16_f32 %0, %1, %2" : "=v"(r) : "v"(lo), "v"(hi)); return r; }
;     __device__ __forceinline__ void operator()(const f32x4 (&acc)[2][2][4][2], const Unit& u, int wr, int wc, int fr, int fq) const {
;         const int lane = fr + 16 * fq, r = lane >> 2, p = lane & 3; PG8_LAS unsigned char* stg = lds + STG_OFF + (wr * 4 + wc) * STG_WAVE;
; #pragma unroll
;         for (int ai = 0; ai < 2; ++ai)
; #pragma unroll
;             for (int m = 0; m < 4; ++m) {
;                 const int row = u.pm * BM + ai * HALF + wr * 64 + m * 16 + r; float q = 0.f;
; #pragma unroll
;                 for (int bj = 0; bj < 2; ++bj) {
;                     const size_t off = (size_t)row * 2048 + u.pn * BM + wc * 64 + bj * 32 + 8 * p;
;                     f32x4 b0, b1;
;                     if (BASE_F32) { b0 = *(const f32x4*)((const float*)base + off); b1 = *(const f32x4*)((const float*)base + off + 4); }
;                     else { const u32x4 bb = *(const u32x4*)((const bf16_t*)base + off);
;                         b0 = (f32x4){__uint_as_float(bb.x << 16), __uint_as_float(bb.x & 0xffff0000u), __uint_as_float(bb.y << 16), __uint_as_float(bb.y & 0xffff0000u)};
;                         b1 = (f32x4){__uint_as_float(bb.z << 16), __uint_as_float(bb.z & 0xffff0000u), __uint_as_float(bb.w << 16), __uint_as_float(bb.w & 0xffff0000u)}; }
; #pragma unroll
;                     for (int n = 0; n < 2; ++n) *(PG8_LAS f32x4*)(stg + fr * STG_ROW + n * 64 + fq * 16) = acc[ai][bj][m][n];
;                     const f32x4 v0 = *(const PG8_LAS f32x4*)(stg + r * STG_ROW + p * 32) + b0, v1 = *(const PG8_LAS f32x4*)(stg + r * STG_ROW + p * 32 + 16) + b1;
;                     q += ((v0[0] * v0[0] + v0[1] * v0[1]) + (v0[2] * v0[2] + v0[3] * v0[3])) + ((v1[0] * v1[0] + v1[1] * v1[1]) + (v1[2] * v1[2] + v1[3] * v1[3]));
;                     u32x4 w; w.x = cvt_pk_bf16(v0[0], v0[1]); w.y = cvt_pk_bf16(v0[2], v0[3]); w.z = cvt_pk_bf16(v1[0], v1[1]); w.w = cvt_pk_bf16(v1[2], v1[3]);
;                     *(u32x4*)(out + off) = w;
;                 }
;                 q += __shfl_xor(q, 1); q += __shfl_xor(q, 2);
;                 if (p == 0) atomicAdd(ssn + row, (u64)(q * SS_SCALE));
.LBB0_477:
	ds_write_b128 v156, v[124:127]
	ds_write_b128 v156, v[120:123] offset:64
	ds_read_b128 v[120:123], v157
	ds_read_b128 v[124:127], v157 offset:16
	ds_write_b128 v156, v[116:119]
	ds_write_b128 v156, v[112:115] offset:64
	ds_read_b128 v[112:115], v157
	ds_read_b128 v[116:119], v157 offset:16
	s_waitcnt vmcnt(15) lgkmcnt(4)
	v_lshlrev_b32_e32 v236, 16, v160
	v_and_b32_e32 v237, 0xffff0000, v160
	v_lshlrev_b32_e32 v238, 16, v161
	v_and_b32_e32 v239, 0xffff0000, v161
	v_lshlrev_b32_e32 v240, 16, v162
	v_and_b32_e32 v241, 0xffff0000, v162
	v_lshlrev_b32_e32 v242, 16, v163
	v_and_b32_e32 v243, 0xffff0000, v163
	v_pk_add_f32 v[120:121], v[120:121], v[236:237]
	v_pk_add_f32 v[122:123], v[122:123], v[238:239]
	v_pk_add_f32 v[124:125], v[124:125], v[240:241]
	v_pk_add_f32 v[126:127], v[126:127], v[242:243]
	v_mul_f32_e32 v236, v121, v121
	v_mul_f32_e32 v237, v123, v123
	v_mul_f32_e32 v238, v125, v125
	v_mul_f32_e32 v239, v127, v127
	v_fmac_f32_e32 v236, v120, v120
	v_fmac_f32_e32 v237, v122, v122
	v_fmac_f32_e32 v238, v124, v124
	v_fmac_f32_e32 v239, v126, v126
	v_cvt_pk_bf16_f32 v120, v120, v121
	v_cvt_pk_bf16_f32 v121, v122, v123
	v_cvt_pk_bf16_f32 v122, v124, v125
	v_cvt_pk_bf16_f32 v123, v126, v127
	v_add_f32_e32 v236, v236, v237
	v_add_f32_e32 v237, v238, v239
	v_add_f32_e32 v124, v236, v237
	global_store_dwordx4 v159, v[120:123], s[28:29]
	ds_write_b128 v156, v[108:111]
	ds_write_b128 v156, v[104:107] offset:64
	ds_read_b128 v[104:107], v157
	ds_read_b128 v[108:111], v157 offset:16
	s_waitcnt vmcnt(15) lgkmcnt(4)
	v_lshlrev_b32_e32 v236, 16, v164
	v_and_b32_e32 v237, 0xffff0000, v164
	v_lshlrev_b32_e32 v238, 16, v165
	v_and_b32_e32 v239, 0xffff0000, v165
	v_lshlrev_b32_e32 v240, 16, v166
	v_and_b32_e32 v241, 0xffff0000, v166
	v_lshlrev_b32_e32 v242, 16, v167
	v_and_b32_e32 v243, 0xffff0000, v167
	v_pk_add_f32 v[112:113], v[112:113], v[236:237]
	v_pk_add_f32 v[114:115], v[114:115], v[238:239]
	v_pk_add_f32 v[116:117], v[116:117], v[240:241]
	v_pk_add_f32 v[118:119], v[118:119], v[242:243]
	v_mul_f32_e32 v236, v113, v113
	v_mul_f32_e32 v237, v115, v115
	v_mul_f32_e32 v238, v117, v117
	v_mul_f32_e32 v239, v119, v119
	v_fmac_f32_e32 v236, v112, v112
	v_fmac_f32_e32 v237, v114, v114
	v_fmac_f32_e32 v238, v116, v116
	v_fmac_f32_e32 v239, v118, v118
	v_cvt_pk_bf16_f32 v112, v112, v113
	v_cvt_pk_bf16_f32 v113, v114, v115
	v_cvt_pk_bf16_f32 v114, v116, v117
	v_cvt_pk_bf16_f32 v115, v118, v119
	v_add_f32_e32 v236, v236, v237
	v_add_f32_e32 v237, v238, v239
	v_add_f32_e32 v116, v236, v237
	global_store_dwordx4 v159, v[112:115], s[28:29] offset:64
	v_add_f32_e32 v117, v124, v116
	s_nop 1
	v_add_f32_dpp v118, v117, v117 quad_perm:[1,0,3,2] row_mask:0xf bank_mask:0xf
	s_nop 1
	v_add_f32_dpp v119, v118, v118 quad_perm:[2,3,0,1] row_mask:0xf bank_mask:0xf
	v_mul_f32_e32 v126, 0x49800000, v119
	v_trunc_f32_e32 v126, v126
	v_mul_f32_e32 v127, 0x2f800000, v126
	v_floor_f32_e32 v127, v127
	v_fmac_f32_e32 v126, 0xcf800000, v127
	v_cvt_u32_f32_e32 v126, v126
	v_cvt_u32_f32_e32 v127, v127
	ds_write_b128 v156, v[100:103]
	ds_write_b128 v156, v[96:99] offset:64
	ds_read_b128 v[96:99], v157
	ds_read_b128 v[100:103], v157 offset:16
	s_waitcnt vmcnt(15) lgkmcnt(4)
	v_lshlrev_b32_e32 v236, 16, v168
	v_and_b32_e32 v237, 0xffff0000, v168
	v_lshlrev_b32_e32 v238, 16, v169
	v_and_b32_e32 v239, 0xffff0000, v169
	v_lshlrev_b32_e32 v240, 16, v170
	v_and_b32_e32 v241, 0xffff0000, v170
	v_lshlrev_b32_e32 v242, 16, v171
	v_and_b32_e32 v243, 0xffff0000, v171
	v_pk_add_f32 v[104:105], v[104:105], v[236:237]
	v_pk_add_f32 v[106:107], v[106:107], v[238:239]
	v_pk_add_f32 v[108:109], v[108:109], v[240:241]
	v_pk_add_f32 v[110:111], v[110:111], v[242:243]
	v_mul_f32_e32 v236, v105, v105
	v_mul_f32_e32 v237, v107, v107
	v_mul_f32_e32 v238, v109, v109
	v_mul_f32_e32 v239, v111, v111
	v_fmac_f32_e32 v236, v104, v104
	v_fmac_f32_e32 v237, v106, v106
	v_fmac_f32_e32 v238, v108, v108
	v_fmac_f32_e32 v239, v110, v110
	v_cvt_pk_bf16_f32 v104, v104, v105
	v_cvt_pk_bf16_f32 v105, v106, v107
	v_cvt_pk_bf16_f32 v106, v108, v109
	v_cvt_pk_bf16_f32 v107, v110, v111
	v_add_f32_e32 v236, v236, v237
	v_add_f32_e32 v237, v238, v239
	v_add_f32_e32 v108, v236, v237
	v_add_u32_e32 v147, 0x10000, v159
	global_store_dwordx4 v147, v[104:107], s[28:29]
	ds_write_b128 v156, v[92:95]
	ds_write_b128 v156, v[88:91] offset:64
	ds_read_b128 v[88:91], v157
	ds_read_b128 v[92:95], v157 offset:16
	s_waitcnt vmcnt(15) lgkmcnt(4)
	v_lshlrev_b32_e32 v236, 16, v172
	v_and_b32_e32 v237, 0xffff0000, v172
	v_lshlrev_b32_e32 v238, 16, v173
	v_and_b32_e32 v239, 0xffff0000, v173
	v_lshlrev_b32_e32 v240, 16, v174
	v_and_b32_e32 v241, 0xffff0000, v174
	v_lshlrev_b32_e32 v242, 16, v175
	v_and_b32_e32 v243, 0xffff0000, v175
	v_pk_add_f32 v[96:97], v[96:97], v[236:237]
	v_pk_add_f32 v[98:99], v[98:99], v[238:239]
	v_pk_add_f32 v[100:101], v[100:101], v[240:241]
	v_pk_add_f32 v[102:103], v[102:103], v[242:243]
	v_mul_f32_e32 v236, v97, v97
	v_mul_f32_e32 v237, v99, v99
	v_mul_f32_e32 v238, v101, v101
	v_mul_f32_e32 v239, v103, v103
	v_fmac_f32_e32 v236, v96, v96
	v_fmac_f32_e32 v237, v98, v98
	v_fmac_f32_e32 v238, v100, v100
	v_fmac_f32_e32 v239, v102, v102
	v_cvt_pk_bf16_f32 v96, v96, v97
	v_cvt_pk_bf16_f32 v97, v98, v99
	v_cvt_pk_bf16_f32 v98, v100, v101
	v_cvt_pk_bf16_f32 v99, v102, v103
	v_add_f32_e32 v236, v236, v237
	v_add_f32_e32 v237, v238, v239
	v_add_f32_e32 v100, v236, v237
	global_store_dwordx4 v147, v[96:99], s[28:29] offset:64
	v_add_f32_e32 v101, v108, v100
	s_nop 1
	v_add_f32_dpp v102, v101, v101 quad_perm:[1,0,3,2] row_mask:0xf bank_mask:0xf
	s_nop 1
	v_add_f32_dpp v103, v102, v102 quad_perm:[2,3,0,1] row_mask:0xf bank_mask:0xf
	v_mul_f32_e32 v110, 0x49800000, v103
	v_trunc_f32_e32 v110, v110
	v_mul_f32_e32 v111, 0x2f800000, v110
	v_floor_f32_e32 v111, v111
	v_fmac_f32_e32 v110, 0xcf800000, v111
	v_cvt_u32_f32_e32 v110, v110
	v_cvt_u32_f32_e32 v111, v111
	ds_write_b128 v156, v[84:87]
	ds_write_b128 v156, v[80:83] offset:64
	ds_read_b128 v[80:83], v157
	ds_read_b128 v[84:87], v157 offset:16
	s_waitcnt vmcnt(15) lgkmcnt(4)
; #define PG8_LAS __attribute__((address_space(3)))
; __device__ __forceinline__ unsigned cvt_pk_bf16(float lo, float hi) { unsigned r; asm volatile("v_cvt_pk_bf16_f32 %0, %1, %2" : "=v"(r) : "v"(lo), "v"(hi)); return r; }
;     __device__ __forceinline__ void operator()(const f32x4 (&acc)[2][2][4][2], const Unit& u, int wr, int wc, int fr, int fq) const {
;         const int lane = fr + 16 * fq, r = lane >> 2, p = lane & 3; PG8_LAS unsigned char* stg = lds + STG_OFF + (wr * 4 + wc) * STG_WAVE;
; #pragma unroll
;         for (int ai = 0; ai < 2; ++ai)
; #pragma unroll
;             for (int m = 0; m < 4; ++m) {
;                 const int row = u.pm * BM + ai * HALF + wr * 64 + m * 16 + r; float q = 0.f;
; #pragma unroll
;                 for (int bj = 0; bj < 2; ++bj) {
;                     const size_t off = (size_t)row * 2048 + u.pn * BM + wc * 64 + bj * 32 + 8 * p;
;                     f32x4 b0, b1;
;                     if (BASE_F32) { b0 = *(const f32x4*)((const float*)base + off); b1 = *(const f32x4*)((const float*)base + off + 4); }
;                     else { const u32x4 bb = *(const u32x4*)((const bf16_t*)base + off);
;                         b0 = (f32x4){__uint_as_float(bb.x << 16), __uint_as_float(bb.x & 0xffff0000u), __uint_as_float(bb.y << 16), __uint_as_float(bb.y & 0xffff0000u)};
;                         b1 = (f32x4){__uint_as_float(bb.z << 16), __uint_as_float(bb.z & 0xffff0000u), __uint_as_float(bb.w << 16), __uint_as_float(bb.w & 0xffff0000u)}; }
; #pragma unroll
;                     for (int n = 0; n < 2; ++n) *(PG8_LAS f32x4*)(stg + fr * STG_ROW + n * 64 + fq * 16) = acc[ai][bj][m][n];
;                     const f32x4 v0 = *(const PG8_LAS f32x4*)(stg + r * STG_ROW + p * 32) + b0, v1 = *(const PG8_LAS f32x4*)(stg + r * STG_ROW + p * 32 + 16) + b1;
;                     q += ((v0[0] * v0[0] + v0[1] * v0[1]) + (v0[2] * v0[2] + v0[3] * v0[3])) + ((v1[0] * v1[0] + v1[1] * v1[1]) + (v1[2] * v1[2] + v1[3] * v1[3]));
;                     u32x4 w; w.x = cvt_pk_bf16(v0[0], v0[1]); w.y = cvt_pk_bf16(v0[2], v0[3]); w.z = cvt_pk_bf16(v1[0], v1[1]); w.w = cvt_pk_bf16(v1[2], v1[3]);
;                     *(u32x4*)(out + off) = w;
;                 }
;                 q += __shfl_xor(q, 1); q += __shfl_xor(q, 2);
;                 if (p == 0) atomicAdd(ssn + row, (u64)(q * SS_SCALE));
	v_lshlrev_b32_e32 v236, 16, v176
	v_and_b32_e32 v237, 0xffff0000, v176
	v_lshlrev_b32_e32 v238, 16, v177
	v_and_b32_e32 v239, 0xffff0000, v177
	v_lshlrev_b32_e32 v240, 16, v178
	v_and_b32_e32 v241, 0xffff0000, v178
	v_lshlrev_b32_e32 v242, 16, v179
	v_and_b32_e32 v243, 0xffff0000, v179
	v_pk_add_f32 v[88:89], v[88:89], v[236:237]
	v_pk_add_f32 v[90:91], v[90:91], v[238:239]
	v_pk_add_f32 v[92:93], v[92:93], v[240:241]
	v_pk_add_f32 v[94:95], v[94:95], v[242:243]
	v_mul_f32_e32 v236, v89, v89
	v_mul_f32_e32 v237, v91, v91
	v_mul_f32_e32 v238, v93, v93
	v_mul_f32_e32 v239, v95, v95
	v_fmac_f32_e32 v236, v88, v88
	v_fmac_f32_e32 v237, v90, v90
	v_fmac_f32_e32 v238, v92, v92
	v_fmac_f32_e32 v239, v94, v94
	v_cvt_pk_bf16_f32 v88, v88, v89
	v_cvt_pk_bf16_f32 v89, v90, v91
	v_cvt_pk_bf16_f32 v90, v92, v93
	v_cvt_pk_bf16_f32 v91, v94, v95
	v_add_f32_e32 v236, v236, v237
	v_add_f32_e32 v237, v238, v239
	v_add_f32_e32 v92, v236, v237
	v_add_u32_e32 v146, 0x20000, v159
	global_store_dwordx4 v146, v[88:91], s[28:29]
	ds_write_b128 v156, v[76:79]
	ds_write_b128 v156, v[72:75] offset:64
	ds_read_b128 v[72:75], v157
	ds_read_b128 v[76:79], v157 offset:16
	s_waitcnt vmcnt(15) lgkmcnt(4)
	v_lshlrev_b32_e32 v236, 16, v180
	v_and_b32_e32 v237, 0xffff0000, v180
	v_lshlrev_b32_e32 v238, 16, v181
	v_and_b32_e32 v239, 0xffff0000, v181
	v_lshlrev_b32_e32 v240, 16, v182
	v_and_b32_e32 v241, 0xffff0000, v182
	v_lshlrev_b32_e32 v242, 16, v183
	v_and_b32_e32 v243, 0xffff0000, v183
	v_pk_add_f32 v[80:81], v[80:81], v[236:237]
	v_pk_add_f32 v[82:83], v[82:83], v[238:239]
	v_pk_add_f32 v[84:85], v[84:85], v[240:241]
	v_pk_add_f32 v[86:87], v[86:87], v[242:243]
	v_mul_f32_e32 v236, v81, v81
	v_mul_f32_e32 v237, v83, v83
	v_mul_f32_e32 v238, v85, v85
	v_mul_f32_e32 v239, v87, v87
	v_fmac_f32_e32 v236, v80, v80
	v_fmac_f32_e32 v237, v82, v82
	v_fmac_f32_e32 v238, v84, v84
	v_fmac_f32_e32 v239, v86, v86
	v_cvt_pk_bf16_f32 v80, v80, v81
	v_cvt_pk_bf16_f32 v81, v82, v83
	v_cvt_pk_bf16_f32 v82, v84, v85
	v_cvt_pk_bf16_f32 v83, v86, v87
	v_add_f32_e32 v236, v236, v237
	v_add_f32_e32 v237, v238, v239
	v_add_f32_e32 v84, v236, v237
	global_store_dwordx4 v146, v[80:83], s[28:29] offset:64
	v_add_f32_e32 v85, v92, v84
	s_nop 1
	v_add_f32_dpp v86, v85, v85 quad_perm:[1,0,3,2] row_mask:0xf bank_mask:0xf
	s_nop 1
	v_add_f32_dpp v87, v86, v86 quad_perm:[2,3,0,1] row_mask:0xf bank_mask:0xf
	v_mul_f32_e32 v94, 0x49800000, v87
	v_trunc_f32_e32 v94, v94
	v_mul_f32_e32 v95, 0x2f800000, v94
	v_floor_f32_e32 v95, v95
	v_fmac_f32_e32 v94, 0xcf800000, v95
	v_cvt_u32_f32_e32 v94, v94
	v_cvt_u32_f32_e32 v95, v95
	ds_write_b128 v156, v[68:71]
	ds_write_b128 v156, v[64:67] offset:64
	ds_read_b128 v[64:67], v157
	ds_read_b128 v[68:71], v157 offset:16
	s_waitcnt vmcnt(15) lgkmcnt(4)
	v_lshlrev_b32_e32 v236, 16, v184
	v_and_b32_e32 v237, 0xffff0000, v184
	v_lshlrev_b32_e32 v238, 16, v185
	v_and_b32_e32 v239, 0xffff0000, v185
	v_lshlrev_b32_e32 v240, 16, v186
	v_and_b32_e32 v241, 0xffff0000, v186
	v_lshlrev_b32_e32 v242, 16, v187
	v_and_b32_e32 v243, 0xffff0000, v187
	v_pk_add_f32 v[72:73], v[72:73], v[236:237]
	v_pk_add_f32 v[74:75], v[74:75], v[238:239]
	v_pk_add_f32 v[76:77], v[76:77], v[240:241]
	v_pk_add_f32 v[78:79], v[78:79], v[242:243]
	v_mul_f32_e32 v236, v73, v73
	v_mul_f32_e32 v237, v75, v75
	v_mul_f32_e32 v238, v77, v77
	v_mul_f32_e32 v239, v79, v79
	v_fmac_f32_e32 v236, v72, v72
	v_fmac_f32_e32 v237, v74, v74
	v_fmac_f32_e32 v238, v76, v76
	v_fmac_f32_e32 v239, v78, v78
	v_cvt_pk_bf16_f32 v72, v72, v73
	v_cvt_pk_bf16_f32 v73, v74, v75
	v_cvt_pk_bf16_f32 v74, v76, v77
	v_cvt_pk_bf16_f32 v75, v78, v79
	v_add_f32_e32 v236, v236, v237
	v_add_f32_e32 v237, v238, v239
	v_add_f32_e32 v76, v236, v237
	v_add_u32_e32 v147, 0x30000, v159
	global_store_dwordx4 v147, v[72:75], s[28:29]
	ds_write_b128 v156, v[60:63]
	ds_write_b128 v156, v[56:59] offset:64
	ds_read_b128 v[56:59], v157
	ds_read_b128 v[60:63], v157 offset:16
	s_waitcnt vmcnt(15) lgkmcnt(4)
	v_lshlrev_b32_e32 v236, 16, v188
	v_and_b32_e32 v237, 0xffff0000, v188
	v_lshlrev_b32_e32 v238, 16, v189
	v_and_b32_e32 v239, 0xffff0000, v189
	v_lshlrev_b32_e32 v240, 16, v190
	v_and_b32_e32 v241, 0xffff0000, v190
	v_lshlrev_b32_e32 v242, 16, v191
	v_and_b32_e32 v243, 0xffff0000, v191
	v_pk_add_f32 v[64:65], v[64:65], v[236:237]
	v_pk_add_f32 v[66:67], v[66:67], v[238:239]
	v_pk_add_f32 v[68:69], v[68:69], v[240:241]
	v_pk_add_f32 v[70:71], v[70:71], v[242:243]
	v_mul_f32_e32 v236, v65, v65
	v_mul_f32_e32 v237, v67, v67
	v_mul_f32_e32 v238, v69, v69
	v_mul_f32_e32 v239, v71, v71
	v_fmac_f32_e32 v236, v64, v64
	v_fmac_f32_e32 v237, v66, v66
	v_fmac_f32_e32 v238, v68, v68
	v_fmac_f32_e32 v239, v70, v70
	v_cvt_pk_bf16_f32 v64, v64, v65
	v_cvt_pk_bf16_f32 v65, v66, v67
	v_cvt_pk_bf16_f32 v66, v68, v69
	v_cvt_pk_bf16_f32 v67, v70, v71
	v_add_f32_e32 v236, v236, v237
	v_add_f32_e32 v237, v238, v239
	v_add_f32_e32 v68, v236, v237
	global_store_dwordx4 v147, v[64:67], s[28:29] offset:64
	v_add_f32_e32 v69, v76, v68
	s_nop 1
	v_add_f32_dpp v70, v69, v69 quad_perm:[1,0,3,2] row_mask:0xf bank_mask:0xf
	s_nop 1
	v_add_f32_dpp v71, v70, v70 quad_perm:[2,3,0,1] row_mask:0xf bank_mask:0xf
	v_mul_f32_e32 v78, 0x49800000, v71
	v_trunc_f32_e32 v78, v78
	v_mul_f32_e32 v79, 0x2f800000, v78
	v_floor_f32_e32 v79, v79
	v_fmac_f32_e32 v78, 0xcf800000, v79
	v_cvt_u32_f32_e32 v78, v78
	v_cvt_u32_f32_e32 v79, v79
	ds_write_b128 v156, v[52:55]
	ds_write_b128 v156, v[48:51] offset:64
	ds_read_b128 v[48:51], v157
	ds_read_b128 v[52:55], v157 offset:16
	s_waitcnt vmcnt(15) lgkmcnt(4)
; #define PG8_LAS __attribute__((address_space(3)))
; __device__ __forceinline__ unsigned cvt_pk_bf16(float lo, float hi) { unsigned r; asm volatile("v_cvt_pk_bf16_f32 %0, %1, %2" : "=v"(r) : "v"(lo), "v"(hi)); return r; }
;     __device__ __forceinline__ void operator()(const f32x4 (&acc)[2][2][4][2], const Unit& u, int wr, int wc, int fr, int fq) const {
;         const int lane = fr + 16 * fq, r = lane >> 2, p = lane & 3; PG8_LAS unsigned char* stg = lds + STG_OFF + (wr * 4 + wc) * STG_WAVE;
; #pragma unroll
;         for (int ai = 0; ai < 2; ++ai)
; #pragma unroll
;             for (int m = 0; m < 4; ++m) {
;                 const int row = u.pm * BM + ai * HALF + wr * 64 + m * 16 + r; float q = 0.f;
; #pragma unroll
;                 for (int bj = 0; bj < 2; ++bj) {
;                     const size_t off = (size_t)row * 2048 + u.pn * BM + wc * 64 + bj * 32 + 8 * p;
;                     f32x4 b0, b1;
;                     if (BASE_F32) { b0 = *(const f32x4*)((const float*)base + off); b1 = *(const f32x4*)((const float*)base + off + 4); }
;                     else { const u32x4 bb = *(const u32x4*)((const bf16_t*)base + off);
;                         b0 = (f32x4){__uint_as_float(bb.x << 16), __uint_as_float(bb.x & 0xffff0000u), __uint_as_float(bb.y << 16), __uint_as_float(bb.y & 0xffff0000u)};
;                         b1 = (f32x4){__uint_as_float(bb.z << 16), __uint_as_float(bb.z & 0xffff0000u), __uint_as_float(bb.w << 16), __uint_as_float(bb.w & 0xffff0000u)}; }
; #pragma unroll
;                     for (int n = 0; n < 2; ++n) *(PG8_LAS f32x4*)(stg + fr * STG_ROW + n * 64 + fq * 16) = acc[ai][bj][m][n];
;                     const f32x4 v0 = *(const PG8_LAS f32x4*)(stg + r * STG_ROW + p * 32) + b0, v1 = *(const PG8_LAS f32x4*)(stg + r * STG_ROW + p * 32 + 16) + b1;
;                     q += ((v0[0] * v0[0] + v0[1] * v0[1]) + (v0[2] * v0[2] + v0[3] * v0[3])) + ((v1[0] * v1[0] + v1[1] * v1[1]) + (v1[2] * v1[2] + v1[3] * v1[3]));
;                     u32x4 w; w.x = cvt_pk_bf16(v0[0], v0[1]); w.y = cvt_pk_bf16(v0[2], v0[3]); w.z = cvt_pk_bf16(v1[0], v1[1]); w.w = cvt_pk_bf16(v1[2], v1[3]);
;                     *(u32x4*)(out + off) = w;
;                 }
;                 q += __shfl_xor(q, 1); q += __shfl_xor(q, 2);
;                 if (p == 0) atomicAdd(ssn + row, (u64)(q * SS_SCALE));
	v_lshlrev_b32_e32 v236, 16, v192
	v_and_b32_e32 v237, 0xffff0000, v192
	v_lshlrev_b32_e32 v238, 16, v193
	v_and_b32_e32 v239, 0xffff0000, v193
	v_lshlrev_b32_e32 v240, 16, v194
	v_and_b32_e32 v241, 0xffff0000, v194
	v_lshlrev_b32_e32 v242, 16, v195
	v_and_b32_e32 v243, 0xffff0000, v195
	v_pk_add_f32 v[56:57], v[56:57], v[236:237]
	v_pk_add_f32 v[58:59], v[58:59], v[238:239]
	v_pk_add_f32 v[60:61], v[60:61], v[240:241]
	v_pk_add_f32 v[62:63], v[62:63], v[242:243]
	v_mul_f32_e32 v236, v57, v57
	v_mul_f32_e32 v237, v59, v59
	v_mul_f32_e32 v238, v61, v61
	v_mul_f32_e32 v239, v63, v63
	v_fmac_f32_e32 v236, v56, v56
	v_fmac_f32_e32 v237, v58, v58
	v_fmac_f32_e32 v238, v60, v60
	v_fmac_f32_e32 v239, v62, v62
	v_cvt_pk_bf16_f32 v56, v56, v57
	v_cvt_pk_bf16_f32 v57, v58, v59
	v_cvt_pk_bf16_f32 v58, v60, v61
	v_cvt_pk_bf16_f32 v59, v62, v63
	v_add_f32_e32 v236, v236, v237
	v_add_f32_e32 v237, v238, v239
	v_add_f32_e32 v60, v236, v237
	v_add_u32_e32 v146, 0x80000, v159
	global_store_dwordx4 v146, v[56:59], s[28:29]
	ds_write_b128 v156, v[44:47]
	ds_write_b128 v156, v[40:43] offset:64
	ds_read_b128 v[40:43], v157
	ds_read_b128 v[44:47], v157 offset:16
	s_waitcnt vmcnt(15) lgkmcnt(4)
	v_lshlrev_b32_e32 v236, 16, v196
	v_and_b32_e32 v237, 0xffff0000, v196
	v_lshlrev_b32_e32 v238, 16, v197
	v_and_b32_e32 v239, 0xffff0000, v197
	v_lshlrev_b32_e32 v240, 16, v198
	v_and_b32_e32 v241, 0xffff0000, v198
	v_lshlrev_b32_e32 v242, 16, v199
	v_and_b32_e32 v243, 0xffff0000, v199
	v_pk_add_f32 v[48:49], v[48:49], v[236:237]
	v_pk_add_f32 v[50:51], v[50:51], v[238:239]
	v_pk_add_f32 v[52:53], v[52:53], v[240:241]
	v_pk_add_f32 v[54:55], v[54:55], v[242:243]
	v_mul_f32_e32 v236, v49, v49
	v_mul_f32_e32 v237, v51, v51
	v_mul_f32_e32 v238, v53, v53
	v_mul_f32_e32 v239, v55, v55
	v_fmac_f32_e32 v236, v48, v48
	v_fmac_f32_e32 v237, v50, v50
	v_fmac_f32_e32 v238, v52, v52
	v_fmac_f32_e32 v239, v54, v54
	v_cvt_pk_bf16_f32 v48, v48, v49
	v_cvt_pk_bf16_f32 v49, v50, v51
	v_cvt_pk_bf16_f32 v50, v52, v53
	v_cvt_pk_bf16_f32 v51, v54, v55
	v_add_f32_e32 v236, v236, v237
	v_add_f32_e32 v237, v238, v239
	v_add_f32_e32 v52, v236, v237
	global_store_dwordx4 v146, v[48:51], s[28:29] offset:64
	v_add_f32_e32 v53, v60, v52
	s_nop 1
	v_add_f32_dpp v54, v53, v53 quad_perm:[1,0,3,2] row_mask:0xf bank_mask:0xf
	s_nop 1
	v_add_f32_dpp v55, v54, v54 quad_perm:[2,3,0,1] row_mask:0xf bank_mask:0xf
	v_mul_f32_e32 v62, 0x49800000, v55
	v_trunc_f32_e32 v62, v62
	v_mul_f32_e32 v63, 0x2f800000, v62
	v_floor_f32_e32 v63, v63
	v_fmac_f32_e32 v62, 0xcf800000, v63
	v_cvt_u32_f32_e32 v62, v62
	v_cvt_u32_f32_e32 v63, v63
	ds_write_b128 v156, v[36:39]
	ds_write_b128 v156, v[32:35] offset:64
	ds_read_b128 v[32:35], v157
	ds_read_b128 v[36:39], v157 offset:16
	s_waitcnt vmcnt(15) lgkmcnt(4)
	v_lshlrev_b32_e32 v236, 16, v200
	v_and_b32_e32 v237, 0xffff0000, v200
	v_lshlrev_b32_e32 v238, 16, v201
	v_and_b32_e32 v239, 0xffff0000, v201
	v_lshlrev_b32_e32 v240, 16, v202
	v_and_b32_e32 v241, 0xffff0000, v202
	v_lshlrev_b32_e32 v242, 16, v203
	v_and_b32_e32 v243, 0xffff0000, v203
	v_pk_add_f32 v[40:41], v[40:41], v[236:237]
	v_pk_add_f32 v[42:43], v[42:43], v[238:239]
	v_pk_add_f32 v[44:45], v[44:45], v[240:241]
	v_pk_add_f32 v[46:47], v[46:47], v[242:243]
	v_mul_f32_e32 v236, v41, v41
	v_mul_f32_e32 v237, v43, v43
	v_mul_f32_e32 v238, v45, v45
	v_mul_f32_e32 v239, v47, v47
	v_fmac_f32_e32 v236, v40, v40
	v_fmac_f32_e32 v237, v42, v42
	v_fmac_f32_e32 v238, v44, v44
	v_fmac_f32_e32 v239, v46, v46
	v_cvt_pk_bf16_f32 v40, v40, v41
	v_cvt_pk_bf16_f32 v41, v42, v43
	v_cvt_pk_bf16_f32 v42, v44, v45
	v_cvt_pk_bf16_f32 v43, v46, v47
	v_add_f32_e32 v236, v236, v237
	v_add_f32_e32 v237, v238, v239
	v_add_f32_e32 v44, v236, v237
	v_add_u32_e32 v147, 0x90000, v159
	global_store_dwordx4 v147, v[40:43], s[28:29]
	ds_write_b128 v156, v[28:31]
	ds_write_b128 v156, v[24:27] offset:64
	ds_read_b128 v[24:27], v157
	ds_read_b128 v[28:31], v157 offset:16
	s_waitcnt vmcnt(15) lgkmcnt(4)
	v_lshlrev_b32_e32 v236, 16, v204
	v_and_b32_e32 v237, 0xffff0000, v204
	v_lshlrev_b32_e32 v238, 16, v205
	v_and_b32_e32 v239, 0xffff0000, v205
	v_lshlrev_b32_e32 v240, 16, v206
	v_and_b32_e32 v241, 0xffff0000, v206
	v_lshlrev_b32_e32 v242, 16, v207
	v_and_b32_e32 v243, 0xffff0000, v207
	v_pk_add_f32 v[32:33], v[32:33], v[236:237]
	v_pk_add_f32 v[34:35], v[34:35], v[238:239]
	v_pk_add_f32 v[36:37], v[36:37], v[240:241]
	v_pk_add_f32 v[38:39], v[38:39], v[242:243]
	v_mul_f32_e32 v236, v33, v33
	v_mul_f32_e32 v237, v35, v35
	v_mul_f32_e32 v238, v37, v37
	v_mul_f32_e32 v239, v39, v39
	v_fmac_f32_e32 v236, v32, v32
	v_fmac_f32_e32 v237, v34, v34
	v_fmac_f32_e32 v238, v36, v36
	v_fmac_f32_e32 v239, v38, v38
	v_cvt_pk_bf16_f32 v32, v32, v33
	v_cvt_pk_bf16_f32 v33, v34, v35
	v_cvt_pk_bf16_f32 v34, v36, v37
	v_cvt_pk_bf16_f32 v35, v38, v39
	v_add_f32_e32 v236, v236, v237
	v_add_f32_e32 v237, v238, v239
	v_add_f32_e32 v36, v236, v237
	global_store_dwordx4 v147, v[32:35], s[28:29] offset:64
	v_add_f32_e32 v37, v44, v36
	s_nop 1
	v_add_f32_dpp v38, v37, v37 quad_perm:[1,0,3,2] row_mask:0xf bank_mask:0xf
	s_nop 1
	v_add_f32_dpp v39, v38, v38 quad_perm:[2,3,0,1] row_mask:0xf bank_mask:0xf
	v_mul_f32_e32 v46, 0x49800000, v39
	v_trunc_f32_e32 v46, v46
	v_mul_f32_e32 v47, 0x2f800000, v46
	v_floor_f32_e32 v47, v47
	v_fmac_f32_e32 v46, 0xcf800000, v47
	v_cvt_u32_f32_e32 v46, v46
	v_cvt_u32_f32_e32 v47, v47
	ds_write_b128 v156, v[20:23]
	ds_write_b128 v156, v[16:19] offset:64
	ds_read_b128 v[16:19], v157
	ds_read_b128 v[20:23], v157 offset:16
	s_waitcnt vmcnt(15) lgkmcnt(4)
; #define PG8_LAS __attribute__((address_space(3)))
; __device__ __forceinline__ unsigned cvt_pk_bf16(float lo, float hi) { unsigned r; asm volatile("v_cvt_pk_bf16_f32 %0, %1, %2" : "=v"(r) : "v"(lo), "v"(hi)); return r; }
;     __device__ __forceinline__ void operator()(const f32x4 (&acc)[2][2][4][2], const Unit& u, int wr, int wc, int fr, int fq) const {
;         const int lane = fr + 16 * fq, r = lane >> 2, p = lane & 3; PG8_LAS unsigned char* stg = lds + STG_OFF + (wr * 4 + wc) * STG_WAVE;
; #pragma unroll
;         for (int ai = 0; ai < 2; ++ai)
; #pragma unroll
;             for (int m = 0; m < 4; ++m) {
;                 const int row = u.pm * BM + ai * HALF + wr * 64 + m * 16 + r; float q = 0.f;
; #pragma unroll
;                 for (int bj = 0; bj < 2; ++bj) {
;                     const size_t off = (size_t)row * 2048 + u.pn * BM + wc * 64 + bj * 32 + 8 * p;
;                     f32x4 b0, b1;
;                     if (BASE_F32) { b0 = *(const f32x4*)((const float*)base + off); b1 = *(const f32x4*)((const float*)base + off + 4); }
;                     else { const u32x4 bb = *(const u32x4*)((const bf16_t*)base + off);
;                         b0 = (f32x4){__uint_as_float(bb.x << 16), __uint_as_float(bb.x & 0xffff0000u), __uint_as_float(bb.y << 16), __uint_as_float(bb.y & 0xffff0000u)};
;                         b1 = (f32x4){__uint_as_float(bb.z << 16), __uint_as_float(bb.z & 0xffff0000u), __uint_as_float(bb.w << 16), __uint_as_float(bb.w & 0xffff0000u)}; }
; #pragma unroll
;                     for (int n = 0; n < 2; ++n) *(PG8_LAS f32x4*)(stg + fr * STG_ROW + n * 64 + fq * 16) = acc[ai][bj][m][n];
;                     const f32x4 v0 = *(const PG8_LAS f32x4*)(stg + r * STG_ROW + p * 32) + b0, v1 = *(const PG8_LAS f32x4*)(stg + r * STG_ROW + p * 32 + 16) + b1;
;                     q += ((v0[0] * v0[0] + v0[1] * v0[1]) + (v0[2] * v0[2] + v0[3] * v0[3])) + ((v1[0] * v1[0] + v1[1] * v1[1]) + (v1[2] * v1[2] + v1[3] * v1[3]));
;                     u32x4 w; w.x = cvt_pk_bf16(v0[0], v0[1]); w.y = cvt_pk_bf16(v0[2], v0[3]); w.z = cvt_pk_bf16(v1[0], v1[1]); w.w = cvt_pk_bf16(v1[2], v1[3]);
;                     *(u32x4*)(out + off) = w;
;                 }
;                 q += __shfl_xor(q, 1); q += __shfl_xor(q, 2);
;                 if (p == 0) atomicAdd(ssn + row, (u64)(q * SS_SCALE));
	v_lshlrev_b32_e32 v236, 16, v212
	v_and_b32_e32 v237, 0xffff0000, v212
	v_lshlrev_b32_e32 v238, 16, v213
	v_and_b32_e32 v239, 0xffff0000, v213
	v_lshlrev_b32_e32 v240, 16, v214
	v_and_b32_e32 v241, 0xffff0000, v214
	v_lshlrev_b32_e32 v242, 16, v215
	v_and_b32_e32 v243, 0xffff0000, v215
	v_pk_add_f32 v[24:25], v[24:25], v[236:237]
	v_pk_add_f32 v[26:27], v[26:27], v[238:239]
	v_pk_add_f32 v[28:29], v[28:29], v[240:241]
	v_pk_add_f32 v[30:31], v[30:31], v[242:243]
	v_mul_f32_e32 v236, v25, v25
	v_mul_f32_e32 v237, v27, v27
	v_mul_f32_e32 v238, v29, v29
	v_mul_f32_e32 v239, v31, v31
	v_fmac_f32_e32 v236, v24, v24
	v_fmac_f32_e32 v237, v26, v26
	v_fmac_f32_e32 v238, v28, v28
	v_fmac_f32_e32 v239, v30, v30
	v_cvt_pk_bf16_f32 v24, v24, v25
	v_cvt_pk_bf16_f32 v25, v26, v27
	v_cvt_pk_bf16_f32 v26, v28, v29
	v_cvt_pk_bf16_f32 v27, v30, v31
	v_add_f32_e32 v236, v236, v237
	v_add_f32_e32 v237, v238, v239
	v_add_f32_e32 v28, v236, v237
	v_add_u32_e32 v146, 0xa0000, v159
	global_store_dwordx4 v146, v[24:27], s[28:29]
	ds_write_b128 v156, v[12:15]
	ds_write_b128 v156, v[8:11] offset:64
	ds_read_b128 v[8:11], v157
	ds_read_b128 v[12:15], v157 offset:16
	s_waitcnt vmcnt(15) lgkmcnt(4)
	v_lshlrev_b32_e32 v236, 16, v216
	v_and_b32_e32 v237, 0xffff0000, v216
	v_lshlrev_b32_e32 v238, 16, v217
	v_and_b32_e32 v239, 0xffff0000, v217
	v_lshlrev_b32_e32 v240, 16, v218
	v_and_b32_e32 v241, 0xffff0000, v218
	v_lshlrev_b32_e32 v242, 16, v219
	v_and_b32_e32 v243, 0xffff0000, v219
	v_pk_add_f32 v[16:17], v[16:17], v[236:237]
	v_pk_add_f32 v[18:19], v[18:19], v[238:239]
	v_pk_add_f32 v[20:21], v[20:21], v[240:241]
	v_pk_add_f32 v[22:23], v[22:23], v[242:243]
	v_mul_f32_e32 v236, v17, v17
	v_mul_f32_e32 v237, v19, v19
	v_mul_f32_e32 v238, v21, v21
	v_mul_f32_e32 v239, v23, v23
	v_fmac_f32_e32 v236, v16, v16
	v_fmac_f32_e32 v237, v18, v18
	v_fmac_f32_e32 v238, v20, v20
	v_fmac_f32_e32 v239, v22, v22
	v_cvt_pk_bf16_f32 v16, v16, v17
	v_cvt_pk_bf16_f32 v17, v18, v19
	v_cvt_pk_bf16_f32 v18, v20, v21
	v_cvt_pk_bf16_f32 v19, v22, v23
	v_add_f32_e32 v236, v236, v237
	v_add_f32_e32 v237, v238, v239
	v_add_f32_e32 v20, v236, v237
	global_store_dwordx4 v146, v[16:19], s[28:29] offset:64
	v_add_f32_e32 v21, v28, v20
	s_nop 1
	v_add_f32_dpp v22, v21, v21 quad_perm:[1,0,3,2] row_mask:0xf bank_mask:0xf
	s_nop 1
	v_add_f32_dpp v23, v22, v22 quad_perm:[2,3,0,1] row_mask:0xf bank_mask:0xf
	v_mul_f32_e32 v30, 0x49800000, v23
	v_trunc_f32_e32 v30, v30
	v_mul_f32_e32 v31, 0x2f800000, v30
	v_floor_f32_e32 v31, v31
	v_fmac_f32_e32 v30, 0xcf800000, v31
	v_cvt_u32_f32_e32 v30, v30
	v_cvt_u32_f32_e32 v31, v31
	ds_write_b128 v156, v[4:7]
	ds_write_b128 v156, v[0:3] offset:64
	ds_read_b128 v[0:3], v157
	ds_read_b128 v[4:7], v157 offset:16
	s_waitcnt vmcnt(15) lgkmcnt(4)
	v_lshlrev_b32_e32 v236, 16, v220
	v_and_b32_e32 v237, 0xffff0000, v220
	v_lshlrev_b32_e32 v238, 16, v221
	v_and_b32_e32 v239, 0xffff0000, v221
	v_lshlrev_b32_e32 v240, 16, v222
	v_and_b32_e32 v241, 0xffff0000, v222
	v_lshlrev_b32_e32 v242, 16, v223
	v_and_b32_e32 v243, 0xffff0000, v223
	v_pk_add_f32 v[8:9], v[8:9], v[236:237]
	v_pk_add_f32 v[10:11], v[10:11], v[238:239]
	v_pk_add_f32 v[12:13], v[12:13], v[240:241]
	v_pk_add_f32 v[14:15], v[14:15], v[242:243]
	v_mul_f32_e32 v236, v9, v9
	v_mul_f32_e32 v237, v11, v11
	v_mul_f32_e32 v238, v13, v13
	v_mul_f32_e32 v239, v15, v15
	v_fmac_f32_e32 v236, v8, v8
	v_fmac_f32_e32 v237, v10, v10
	v_fmac_f32_e32 v238, v12, v12
	v_fmac_f32_e32 v239, v14, v14
	v_cvt_pk_bf16_f32 v8, v8, v9
	v_cvt_pk_bf16_f32 v9, v10, v11
	v_cvt_pk_bf16_f32 v10, v12, v13
	v_cvt_pk_bf16_f32 v11, v14, v15
	v_add_f32_e32 v236, v236, v237
	v_add_f32_e32 v237, v238, v239
	v_add_f32_e32 v12, v236, v237
	v_add_u32_e32 v147, 0xb0000, v159
	global_store_dwordx4 v147, v[8:11], s[28:29]
	s_waitcnt vmcnt(15) lgkmcnt(0)
	v_lshlrev_b32_e32 v236, 16, v224
	v_and_b32_e32 v237, 0xffff0000, v224
	v_lshlrev_b32_e32 v238, 16, v225
	v_and_b32_e32 v239, 0xffff0000, v225
	v_lshlrev_b32_e32 v240, 16, v226
	v_and_b32_e32 v241, 0xffff0000, v226
	v_lshlrev_b32_e32 v242, 16, v227
	v_and_b32_e32 v243, 0xffff0000, v227
	v_pk_add_f32 v[0:1], v[0:1], v[236:237]
	v_pk_add_f32 v[2:3], v[2:3], v[238:239]
	v_pk_add_f32 v[4:5], v[4:5], v[240:241]
	v_pk_add_f32 v[6:7], v[6:7], v[242:243]
	v_mul_f32_e32 v236, v1, v1
	v_mul_f32_e32 v237, v3, v3
	v_mul_f32_e32 v238, v5, v5
	v_mul_f32_e32 v239, v7, v7
	v_fmac_f32_e32 v236, v0, v0
	v_fmac_f32_e32 v237, v2, v2
	v_fmac_f32_e32 v238, v4, v4
	v_fmac_f32_e32 v239, v6, v6
	v_cvt_pk_bf16_f32 v0, v0, v1
	v_cvt_pk_bf16_f32 v1, v2, v3
	v_cvt_pk_bf16_f32 v2, v4, v5
	v_cvt_pk_bf16_f32 v3, v6, v7
	v_add_f32_e32 v236, v236, v237
	v_add_f32_e32 v237, v238, v239
	v_add_f32_e32 v4, v236, v237
	global_store_dwordx4 v147, v[0:3], s[28:29] offset:64
	v_add_f32_e32 v5, v12, v4
	s_nop 1
	v_add_f32_dpp v6, v5, v5 quad_perm:[1,0,3,2] row_mask:0xf bank_mask:0xf
	s_nop 1
	v_add_f32_dpp v7, v6, v6 quad_perm:[2,3,0,1] row_mask:0xf bank_mask:0xf
	v_mul_f32_e32 v14, 0x49800000, v7
	v_trunc_f32_e32 v14, v14
	v_mul_f32_e32 v15, 0x2f800000, v14
	v_floor_f32_e32 v15, v15
	v_fmac_f32_e32 v14, 0xcf800000, v15
	v_cvt_u32_f32_e32 v14, v14
	v_cvt_u32_f32_e32 v15, v15
	v_and_b32_e32 v236, 3, v252
	v_lshl_add_u32 v237, v236, 7, v208
	v_cmp_eq_u32_e64 s[100:101], 1, v236
	v_cndmask_b32_e64 v126, v126, v110, s[100:101]
	v_cndmask_b32_e64 v127, v127, v111, s[100:101]
	v_cmp_eq_u32_e64 s[100:101], 2, v236
	v_cndmask_b32_e64 v126, v126, v94, s[100:101]
	v_cndmask_b32_e64 v127, v127, v95, s[100:101]
	v_cmp_eq_u32_e64 s[100:101], 3, v236
	v_cndmask_b32_e64 v126, v126, v78, s[100:101]
	v_cndmask_b32_e64 v127, v127, v79, s[100:101]
	global_atomic_add_x2 v237, v[126:127], s[44:45]
	v_cmp_eq_u32_e64 s[100:101], 1, v236
	v_cndmask_b32_e64 v62, v62, v46, s[100:101]
	v_cndmask_b32_e64 v63, v63, v47, s[100:101]
	v_cmp_eq_u32_e64 s[100:101], 2, v236
	v_cndmask_b32_e64 v62, v62, v30, s[100:101]
	v_cndmask_b32_e64 v63, v63, v31, s[100:101]
	v_cmp_eq_u32_e64 s[100:101], 3, v236
	v_cndmask_b32_e64 v62, v62, v14, s[100:101]
	v_cndmask_b32_e64 v63, v63, v15, s[100:101]
	global_atomic_add_x2 v237, v[62:63], s[44:45] offset:1024
	s_and_b64 vcc, exec, s[10:11]
	s_mov_b64 s[10:11], -1
	s_cbranch_vccnz .LBB0_464
	s_andn2_b64 vcc, exec, s[14:15]
	s_cbranch_vccnz .LBB0_463
	s_mov_b32 s98, 1
	s_branch .LBB0_463

; #define PG8_LAS __attribute__((address_space(3)))
; __device__ __forceinline__ unsigned cvt_pk_bf16(float lo, float hi) { unsigned r; asm volatile("v_cvt_pk_bf16_f32 %0, %1, %2" : "=v"(r) : "v"(lo), "v"(hi)); return r; }
;     __device__ __forceinline__ void operator()(const f32x4 (&acc)[2][2][4][2], const Unit& u, int wr, int wc, int fr, int fq) const {
;         const int lane = fr + 16 * fq, r = lane >> 2, p = lane & 3; PG8_LAS unsigned char* stg = lds + STG_OFF + (wr * 4 + wc) * STG_WAVE;
; #pragma unroll
;         for (int ai = 0; ai < 2; ++ai)
; #pragma unroll
;             for (int m = 0; m < 4; ++m) {
;                 const int row = u.pm * BM + ai * HALF + wr * 64 + m * 16 + r; float q = 0.f;
; #pragma unroll
;                 for (int bj = 0; bj < 2; ++bj) {
;                     const size_t off = (size_t)row * 2048 + u.pn * BM + wc * 64 + bj * 32 + 8 * p;
;                     f32x4 b0, b1;
;                     if (BASE_F32) { b0 = *(const f32x4*)((const float*)base + off); b1 = *(const f32x4*)((const float*)base + off + 4); }
;                     else { const u32x4 bb = *(const u32x4*)((const bf16_t*)base + off);
;                         b0 = (f32x4){__uint_as_float(bb.x << 16), __uint_as_float(bb.x & 0xffff0000u), __uint_as_float(bb.y << 16), __uint_as_float(bb.y & 0xffff0000u)};
;                         b1 = (f32x4){__uint_as_float(bb.z << 16), __uint_as_float(bb.z & 0xffff0000u), __uint_as_float(bb.w << 16), __uint_as_float(bb.w & 0xffff0000u)}; }
; #pragma unroll
;                     for (int n = 0; n < 2; ++n) *(PG8_LAS f32x4*)(stg + fr * STG_ROW + n * 64 + fq * 16) = acc[ai][bj][m][n];
;                     const f32x4 v0 = *(const PG8_LAS f32x4*)(stg + r * STG_ROW + p * 32) + b0, v1 = *(const PG8_LAS f32x4*)(stg + r * STG_ROW + p * 32 + 16) + b1;
;                     q += ((v0[0] * v0[0] + v0[1] * v0[1]) + (v0[2] * v0[2] + v0[3] * v0[3])) + ((v1[0] * v1[0] + v1[1] * v1[1]) + (v1[2] * v1[2] + v1[3] * v1[3]));
;                     u32x4 w; w.x = cvt_pk_bf16(v0[0], v0[1]); w.y = cvt_pk_bf16(v0[2], v0[3]); w.z = cvt_pk_bf16(v1[0], v1[1]); w.w = cvt_pk_bf16(v1[2], v1[3]);
;                     *(u32x4*)(out + off) = w;
;                 }
;                 q += __shfl_xor(q, 1); q += __shfl_xor(q, 2);
;                 if (p == 0) atomicAdd(ssn + row, (u64)(q * SS_SCALE));
.LBB0_770:
	ds_write_b128 v156, v[124:127]
	ds_write_b128 v156, v[120:123] offset:64
	ds_read_b128 v[120:123], v157
	ds_read_b128 v[124:127], v157 offset:16
	ds_write_b128 v156, v[116:119]
	ds_write_b128 v156, v[112:115] offset:64
	ds_read_b128 v[112:115], v157
	ds_read_b128 v[116:119], v157 offset:16
	s_waitcnt vmcnt(15) lgkmcnt(4)
	v_lshlrev_b32_e32 v236, 16, v160
	v_and_b32_e32 v237, 0xffff0000, v160
	v_lshlrev_b32_e32 v238, 16, v161
	v_and_b32_e32 v239, 0xffff0000, v161
	v_lshlrev_b32_e32 v240, 16, v162
	v_and_b32_e32 v241, 0xffff0000, v162
	v_lshlrev_b32_e32 v242, 16, v163
	v_and_b32_e32 v243, 0xffff0000, v163
	v_pk_add_f32 v[120:121], v[120:121], v[236:237]
	v_pk_add_f32 v[122:123], v[122:123], v[238:239]
	v_pk_add_f32 v[124:125], v[124:125], v[240:241]
	v_pk_add_f32 v[126:127], v[126:127], v[242:243]
	v_mul_f32_e32 v236, v121, v121
	v_mul_f32_e32 v237, v123, v123
	v_mul_f32_e32 v238, v125, v125
	v_mul_f32_e32 v239, v127, v127
	v_fmac_f32_e32 v236, v120, v120
	v_fmac_f32_e32 v237, v122, v122
	v_fmac_f32_e32 v238, v124, v124
	v_fmac_f32_e32 v239, v126, v126
	v_cvt_pk_bf16_f32 v120, v120, v121
	v_cvt_pk_bf16_f32 v121, v122, v123
	v_cvt_pk_bf16_f32 v122, v124, v125
	v_cvt_pk_bf16_f32 v123, v126, v127
	v_add_f32_e32 v236, v236, v237
	v_add_f32_e32 v237, v238, v239
	v_add_f32_e32 v124, v236, v237
	global_store_dwordx4 v159, v[120:123], s[28:29]
	ds_write_b128 v156, v[108:111]
	ds_write_b128 v156, v[104:107] offset:64
	ds_read_b128 v[104:107], v157
	ds_read_b128 v[108:111], v157 offset:16
	s_waitcnt vmcnt(15) lgkmcnt(4)
	v_lshlrev_b32_e32 v236, 16, v164
	v_and_b32_e32 v237, 0xffff0000, v164
	v_lshlrev_b32_e32 v238, 16, v165
	v_and_b32_e32 v239, 0xffff0000, v165
	v_lshlrev_b32_e32 v240, 16, v166
	v_and_b32_e32 v241, 0xffff0000, v166
	v_lshlrev_b32_e32 v242, 16, v167
	v_and_b32_e32 v243, 0xffff0000, v167
	v_pk_add_f32 v[112:113], v[112:113], v[236:237]
	v_pk_add_f32 v[114:115], v[114:115], v[238:239]
	v_pk_add_f32 v[116:117], v[116:117], v[240:241]
	v_pk_add_f32 v[118:119], v[118:119], v[242:243]
	v_mul_f32_e32 v236, v113, v113
	v_mul_f32_e32 v237, v115, v115
	v_mul_f32_e32 v238, v117, v117
	v_mul_f32_e32 v239, v119, v119
	v_fmac_f32_e32 v236, v112, v112
	v_fmac_f32_e32 v237, v114, v114
	v_fmac_f32_e32 v238, v116, v116
	v_fmac_f32_e32 v239, v118, v118
	v_cvt_pk_bf16_f32 v112, v112, v113
	v_cvt_pk_bf16_f32 v113, v114, v115
	v_cvt_pk_bf16_f32 v114, v116, v117
	v_cvt_pk_bf16_f32 v115, v118, v119
	v_add_f32_e32 v236, v236, v237
	v_add_f32_e32 v237, v238, v239
	v_add_f32_e32 v116, v236, v237
	global_store_dwordx4 v159, v[112:115], s[28:29] offset:64
	v_add_f32_e32 v117, v124, v116
	s_nop 1
	v_add_f32_dpp v118, v117, v117 quad_perm:[1,0,3,2] row_mask:0xf bank_mask:0xf
	s_nop 1
	v_add_f32_dpp v119, v118, v118 quad_perm:[2,3,0,1] row_mask:0xf bank_mask:0xf
	v_mul_f32_e32 v126, 0x49800000, v119
	v_trunc_f32_e32 v126, v126
	v_mul_f32_e32 v127, 0x2f800000, v126
	v_floor_f32_e32 v127, v127
	v_fmac_f32_e32 v126, 0xcf800000, v127
	v_cvt_u32_f32_e32 v126, v126
	v_cvt_u32_f32_e32 v127, v127
	ds_write_b128 v156, v[100:103]
	ds_write_b128 v156, v[96:99] offset:64
	ds_read_b128 v[96:99], v157
	ds_read_b128 v[100:103], v157 offset:16
	s_waitcnt vmcnt(15) lgkmcnt(4)
	v_lshlrev_b32_e32 v236, 16, v168
	v_and_b32_e32 v237, 0xffff0000, v168
	v_lshlrev_b32_e32 v238, 16, v169
	v_and_b32_e32 v239, 0xffff0000, v169
	v_lshlrev_b32_e32 v240, 16, v170
	v_and_b32_e32 v241, 0xffff0000, v170
	v_lshlrev_b32_e32 v242, 16, v171
	v_and_b32_e32 v243, 0xffff0000, v171
	v_pk_add_f32 v[104:105], v[104:105], v[236:237]
	v_pk_add_f32 v[106:107], v[106:107], v[238:239]
	v_pk_add_f32 v[108:109], v[108:109], v[240:241]
	v_pk_add_f32 v[110:111], v[110:111], v[242:243]
	v_mul_f32_e32 v236, v105, v105
	v_mul_f32_e32 v237, v107, v107
	v_mul_f32_e32 v238, v109, v109
	v_mul_f32_e32 v239, v111, v111
	v_fmac_f32_e32 v236, v104, v104
	v_fmac_f32_e32 v237, v106, v106
	v_fmac_f32_e32 v238, v108, v108
	v_fmac_f32_e32 v239, v110, v110
	v_cvt_pk_bf16_f32 v104, v104, v105
	v_cvt_pk_bf16_f32 v105, v106, v107
	v_cvt_pk_bf16_f32 v106, v108, v109
	v_cvt_pk_bf16_f32 v107, v110, v111
	v_add_f32_e32 v236, v236, v237
	v_add_f32_e32 v237, v238, v239
	v_add_f32_e32 v108, v236, v237
	v_add_u32_e32 v147, 0x10000, v159
	global_store_dwordx4 v147, v[104:107], s[28:29]
	ds_write_b128 v156, v[92:95]
	ds_write_b128 v156, v[88:91] offset:64
	ds_read_b128 v[88:91], v157
	ds_read_b128 v[92:95], v157 offset:16
	s_waitcnt vmcnt(15) lgkmcnt(4)
	v_lshlrev_b32_e32 v236, 16, v172
	v_and_b32_e32 v237, 0xffff0000, v172
	v_lshlrev_b32_e32 v238, 16, v173
	v_and_b32_e32 v239, 0xffff0000, v173
	v_lshlrev_b32_e32 v240, 16, v174
	v_and_b32_e32 v241, 0xffff0000, v174
	v_lshlrev_b32_e32 v242, 16, v175
	v_and_b32_e32 v243, 0xffff0000, v175
	v_pk_add_f32 v[96:97], v[96:97], v[236:237]
	v_pk_add_f32 v[98:99], v[98:99], v[238:239]
	v_pk_add_f32 v[100:101], v[100:101], v[240:241]
	v_pk_add_f32 v[102:103], v[102:103], v[242:243]
	v_mul_f32_e32 v236, v97, v97
	v_mul_f32_e32 v237, v99, v99
	v_mul_f32_e32 v238, v101, v101
	v_mul_f32_e32 v239, v103, v103
	v_fmac_f32_e32 v236, v96, v96
	v_fmac_f32_e32 v237, v98, v98
	v_fmac_f32_e32 v238, v100, v100
	v_fmac_f32_e32 v239, v102, v102
	v_cvt_pk_bf16_f32 v96, v96, v97
	v_cvt_pk_bf16_f32 v97, v98, v99
	v_cvt_pk_bf16_f32 v98, v100, v101
	v_cvt_pk_bf16_f32 v99, v102, v103
	v_add_f32_e32 v236, v236, v237
	v_add_f32_e32 v237, v238, v239
	v_add_f32_e32 v100, v236, v237
	global_store_dwordx4 v147, v[96:99], s[28:29] offset:64
	v_add_f32_e32 v101, v108, v100
	s_nop 1
	v_add_f32_dpp v102, v101, v101 quad_perm:[1,0,3,2] row_mask:0xf bank_mask:0xf
	s_nop 1
	v_add_f32_dpp v103, v102, v102 quad_perm:[2,3,0,1] row_mask:0xf bank_mask:0xf
	v_mul_f32_e32 v110, 0x49800000, v103
	v_trunc_f32_e32 v110, v110
	v_mul_f32_e32 v111, 0x2f800000, v110
	v_floor_f32_e32 v111, v111
	v_fmac_f32_e32 v110, 0xcf800000, v111
	v_cvt_u32_f32_e32 v110, v110
	v_cvt_u32_f32_e32 v111, v111
	ds_write_b128 v156, v[84:87]
	ds_write_b128 v156, v[80:83] offset:64
	ds_read_b128 v[80:83], v157
	ds_read_b128 v[84:87], v157 offset:16
	s_waitcnt vmcnt(15) lgkmcnt(4)
; #define PG8_LAS __attribute__((address_space(3)))
; __device__ __forceinline__ unsigned cvt_pk_bf16(float lo, float hi) { unsigned r; asm volatile("v_cvt_pk_bf16_f32 %0, %1, %2" : "=v"(r) : "v"(lo), "v"(hi)); return r; }
;     __device__ __forceinline__ void operator()(const f32x4 (&acc)[2][2][4][2], const Unit& u, int wr, int wc, int fr, int fq) const {
;     ...
;                 for (int bj = 0; bj < 2; ++bj) {
;                     const size_t off = (size_t)row * 2048 + u.pn * BM + wc * 64 + bj * 32 + 8 * p;
;                     f32x4 b0, b1;
;                     if (BASE_F32) { b0 = *(const f32x4*)((const float*)base + off); b1 = *(const f32x4*)((const float*)base + off + 4); }
;                     else { const u32x4 bb = *(const u32x4*)((const bf16_t*)base + off);
;                         b0 = (f32x4){__uint_as_float(bb.x << 16), __uint_as_float(bb.x & 0xffff0000u), __uint_as_float(bb.y << 16), __uint_as_float(bb.y & 0xffff0000u)};
;                         b1 = (f32x4){__uint_as_float(bb.z << 16), __uint_as_float(bb.z & 0xffff0000u), __uint_as_float(bb.w << 16), __uint_as_float(bb.w & 0xffff0000u)}; }
; #pragma unroll
;                     for (int n = 0; n < 2; ++n) *(PG8_LAS f32x4*)(stg + fr * STG_ROW + n * 64 + fq * 16) = acc[ai][bj][m][n];
;                     const f32x4 v0 = *(const PG8_LAS f32x4*)(stg + r * STG_ROW + p * 32) + b0, v1 = *(const PG8_LAS f32x4*)(stg + r * STG_ROW + p * 32 + 16) + b1;
;                     q += ((v0[0] * v0[0] + v0[1] * v0[1]) + (v0[2] * v0[2] + v0[3] * v0[3])) + ((v1[0] * v1[0] + v1[1] * v1[1]) + (v1[2] * v1[2] + v1[3] * v1[3]));
;                     u32x4 w; w.x = cvt_pk_bf16(v0[0], v0[1]); w.y = cvt_pk_bf16(v0[2], v0[3]); w.z = cvt_pk_bf16(v1[0], v1[1]); w.w = cvt_pk_bf16(v1[2], v1[3]);
;                     *(u32x4*)(out + off) = w;
;                 }
;                 q += __shfl_xor(q, 1); q += __shfl_xor(q, 2);
;                 if (p == 0) atomicAdd(ssn + row, (u64)(q * SS_SCALE));
	v_lshlrev_b32_e32 v236, 16, v176
	v_and_b32_e32 v237, 0xffff0000, v176
	v_lshlrev_b32_e32 v238, 16, v177
	v_and_b32_e32 v239, 0xffff0000, v177
	v_lshlrev_b32_e32 v240, 16, v178
	v_and_b32_e32 v241, 0xffff0000, v178
	v_lshlrev_b32_e32 v242, 16, v179
	v_and_b32_e32 v243, 0xffff0000, v179
	v_pk_add_f32 v[88:89], v[88:89], v[236:237]
	v_pk_add_f32 v[90:91], v[90:91], v[238:239]
	v_pk_add_f32 v[92:93], v[92:93], v[240:241]
	v_pk_add_f32 v[94:95], v[94:95], v[242:243]
	v_mul_f32_e32 v236, v89, v89
	v_mul_f32_e32 v237, v91, v91
	v_mul_f32_e32 v238, v93, v93
	v_mul_f32_e32 v239, v95, v95
	v_fmac_f32_e32 v236, v88, v88
	v_fmac_f32_e32 v237, v90, v90
	v_fmac_f32_e32 v238, v92, v92
	v_fmac_f32_e32 v239, v94, v94
	v_cvt_pk_bf16_f32 v88, v88, v89
	v_cvt_pk_bf16_f32 v89, v90, v91
	v_cvt_pk_bf16_f32 v90, v92, v93
	v_cvt_pk_bf16_f32 v91, v94, v95
	v_add_f32_e32 v236, v236, v237
	v_add_f32_e32 v237, v238, v239
	v_add_f32_e32 v92, v236, v237
	v_add_u32_e32 v146, 0x20000, v159
	global_store_dwordx4 v146, v[88:91], s[28:29]
	ds_write_b128 v156, v[76:79]
	ds_write_b128 v156, v[72:75] offset:64
	ds_read_b128 v[72:75], v157
	ds_read_b128 v[76:79], v157 offset:16
	s_waitcnt vmcnt(15) lgkmcnt(4)
	v_lshlrev_b32_e32 v236, 16, v180
	v_and_b32_e32 v237, 0xffff0000, v180
	v_lshlrev_b32_e32 v238, 16, v181
	v_and_b32_e32 v239, 0xffff0000, v181
	v_lshlrev_b32_e32 v240, 16, v182
	v_and_b32_e32 v241, 0xffff0000, v182
	v_lshlrev_b32_e32 v242, 16, v183
	v_and_b32_e32 v243, 0xffff0000, v183
	v_pk_add_f32 v[80:81], v[80:81], v[236:237]
	v_pk_add_f32 v[82:83], v[82:83], v[238:239]
	v_pk_add_f32 v[84:85], v[84:85], v[240:241]
	v_pk_add_f32 v[86:87], v[86:87], v[242:243]
	v_mul_f32_e32 v236, v81, v81
	v_mul_f32_e32 v237, v83, v83
	v_mul_f32_e32 v238, v85, v85
	v_mul_f32_e32 v239, v87, v87
	v_fmac_f32_e32 v236, v80, v80
	v_fmac_f32_e32 v237, v82, v82
	v_fmac_f32_e32 v238, v84, v84
	v_fmac_f32_e32 v239, v86, v86
	v_cvt_pk_bf16_f32 v80, v80, v81
	v_cvt_pk_bf16_f32 v81, v82, v83
	v_cvt_pk_bf16_f32 v82, v84, v85
	v_cvt_pk_bf16_f32 v83, v86, v87
	v_add_f32_e32 v236, v236, v237
	v_add_f32_e32 v237, v238, v239
	v_add_f32_e32 v84, v236, v237
	global_store_dwordx4 v146, v[80:83], s[28:29] offset:64
	v_add_f32_e32 v85, v92, v84
	s_nop 1
	v_add_f32_dpp v86, v85, v85 quad_perm:[1,0,3,2] row_mask:0xf bank_mask:0xf
	s_nop 1
	v_add_f32_dpp v87, v86, v86 quad_perm:[2,3,0,1] row_mask:0xf bank_mask:0xf
	v_mul_f32_e32 v94, 0x49800000, v87
	v_trunc_f32_e32 v94, v94
	v_mul_f32_e32 v95, 0x2f800000, v94
	v_floor_f32_e32 v95, v95
	v_fmac_f32_e32 v94, 0xcf800000, v95
	v_cvt_u32_f32_e32 v94, v94
	v_cvt_u32_f32_e32 v95, v95
	ds_write_b128 v156, v[68:71]
	ds_write_b128 v156, v[64:67] offset:64
	ds_read_b128 v[64:67], v157
	ds_read_b128 v[68:71], v157 offset:16
	s_waitcnt vmcnt(15) lgkmcnt(4)
	v_lshlrev_b32_e32 v236, 16, v184
	v_and_b32_e32 v237, 0xffff0000, v184
	v_lshlrev_b32_e32 v238, 16, v185
	v_and_b32_e32 v239, 0xffff0000, v185
	v_lshlrev_b32_e32 v240, 16, v186
	v_and_b32_e32 v241, 0xffff0000, v186
	v_lshlrev_b32_e32 v242, 16, v187
	v_and_b32_e32 v243, 0xffff0000, v187
	v_pk_add_f32 v[72:73], v[72:73], v[236:237]
	v_pk_add_f32 v[74:75], v[74:75], v[238:239]
	v_pk_add_f32 v[76:77], v[76:77], v[240:241]
	v_pk_add_f32 v[78:79], v[78:79], v[242:243]
	v_mul_f32_e32 v236, v73, v73
	v_mul_f32_e32 v237, v75, v75
	v_mul_f32_e32 v238, v77, v77
	v_mul_f32_e32 v239, v79, v79
	v_fmac_f32_e32 v236, v72, v72
	v_fmac_f32_e32 v237, v74, v74
	v_fmac_f32_e32 v238, v76, v76
	v_fmac_f32_e32 v239, v78, v78
	v_cvt_pk_bf16_f32 v72, v72, v73
	v_cvt_pk_bf16_f32 v73, v74, v75
	v_cvt_pk_bf16_f32 v74, v76, v77
	v_cvt_pk_bf16_f32 v75, v78, v79
	v_add_f32_e32 v236, v236, v237
	v_add_f32_e32 v237, v238, v239
	v_add_f32_e32 v76, v236, v237
	v_add_u32_e32 v147, 0x30000, v159
	global_store_dwordx4 v147, v[72:75], s[28:29]
	ds_write_b128 v156, v[60:63]
	ds_write_b128 v156, v[56:59] offset:64
	ds_read_b128 v[56:59], v157
	ds_read_b128 v[60:63], v157 offset:16
	s_waitcnt vmcnt(15) lgkmcnt(4)
	v_lshlrev_b32_e32 v236, 16, v188
	v_and_b32_e32 v237, 0xffff0000, v188
	v_lshlrev_b32_e32 v238, 16, v189
	v_and_b32_e32 v239, 0xffff0000, v189
	v_lshlrev_b32_e32 v240, 16, v190
	v_and_b32_e32 v241, 0xffff0000, v190
	v_lshlrev_b32_e32 v242, 16, v191
	v_and_b32_e32 v243, 0xffff0000, v191
	v_pk_add_f32 v[64:65], v[64:65], v[236:237]
	v_pk_add_f32 v[66:67], v[66:67], v[238:239]
	v_pk_add_f32 v[68:69], v[68:69], v[240:241]
	v_pk_add_f32 v[70:71], v[70:71], v[242:243]
	v_mul_f32_e32 v236, v65, v65
	v_mul_f32_e32 v237, v67, v67
	v_mul_f32_e32 v238, v69, v69
	v_mul_f32_e32 v239, v71, v71
	v_fmac_f32_e32 v236, v64, v64
	v_fmac_f32_e32 v237, v66, v66
	v_fmac_f32_e32 v238, v68, v68
	v_fmac_f32_e32 v239, v70, v70
	v_cvt_pk_bf16_f32 v64, v64, v65
	v_cvt_pk_bf16_f32 v65, v66, v67
	v_cvt_pk_bf16_f32 v66, v68, v69
	v_cvt_pk_bf16_f32 v67, v70, v71
	v_add_f32_e32 v236, v236, v237
	v_add_f32_e32 v237, v238, v239
	v_add_f32_e32 v68, v236, v237
	global_store_dwordx4 v147, v[64:67], s[28:29] offset:64
	v_add_f32_e32 v69, v76, v68
	s_nop 1
	v_add_f32_dpp v70, v69, v69 quad_perm:[1,0,3,2] row_mask:0xf bank_mask:0xf
	s_nop 1
	v_add_f32_dpp v71, v70, v70 quad_perm:[2,3,0,1] row_mask:0xf bank_mask:0xf
	v_mul_f32_e32 v78, 0x49800000, v71
	v_trunc_f32_e32 v78, v78
	v_mul_f32_e32 v79, 0x2f800000, v78
	v_floor_f32_e32 v79, v79
	v_fmac_f32_e32 v78, 0xcf800000, v79
	v_cvt_u32_f32_e32 v78, v78
	v_cvt_u32_f32_e32 v79, v79
	ds_write_b128 v156, v[52:55]
	ds_write_b128 v156, v[48:51] offset:64
	ds_read_b128 v[48:51], v157
	ds_read_b128 v[52:55], v157 offset:16
	s_waitcnt vmcnt(15) lgkmcnt(4)
; #define PG8_LAS __attribute__((address_space(3)))
; __device__ __forceinline__ unsigned cvt_pk_bf16(float lo, float hi) { unsigned r; asm volatile("v_cvt_pk_bf16_f32 %0, %1, %2" : "=v"(r) : "v"(lo), "v"(hi)); return r; }
;     __device__ __forceinline__ void operator()(const f32x4 (&acc)[2][2][4][2], const Unit& u, int wr, int wc, int fr, int fq) const {
;     ...
;                 for (int bj = 0; bj < 2; ++bj) {
;                     const size_t off = (size_t)row * 2048 + u.pn * BM + wc * 64 + bj * 32 + 8 * p;
;                     f32x4 b0, b1;
;                     if (BASE_F32) { b0 = *(const f32x4*)((const float*)base + off); b1 = *(const f32x4*)((const float*)base + off + 4); }
;                     else { const u32x4 bb = *(const u32x4*)((const bf16_t*)base + off);
;                         b0 = (f32x4){__uint_as_float(bb.x << 16), __uint_as_float(bb.x & 0xffff0000u), __uint_as_float(bb.y << 16), __uint_as_float(bb.y & 0xffff0000u)};
;                         b1 = (f32x4){__uint_as_float(bb.z << 16), __uint_as_float(bb.z & 0xffff0000u), __uint_as_float(bb.w << 16), __uint_as_float(bb.w & 0xffff0000u)}; }
; #pragma unroll
;                     for (int n = 0; n < 2; ++n) *(PG8_LAS f32x4*)(stg + fr * STG_ROW + n * 64 + fq * 16) = acc[ai][bj][m][n];
;                     const f32x4 v0 = *(const PG8_LAS f32x4*)(stg + r * STG_ROW + p * 32) + b0, v1 = *(const PG8_LAS f32x4*)(stg + r * STG_ROW + p * 32 + 16) + b1;
;                     q += ((v0[0] * v0[0] + v0[1] * v0[1]) + (v0[2] * v0[2] + v0[3] * v0[3])) + ((v1[0] * v1[0] + v1[1] * v1[1]) + (v1[2] * v1[2] + v1[3] * v1[3]));
;                     u32x4 w; w.x = cvt_pk_bf16(v0[0], v0[1]); w.y = cvt_pk_bf16(v0[2], v0[3]); w.z = cvt_pk_bf16(v1[0], v1[1]); w.w = cvt_pk_bf16(v1[2], v1[3]);
;                     *(u32x4*)(out + off) = w;
;                 }
;                 q += __shfl_xor(q, 1); q += __shfl_xor(q, 2);
;                 if (p == 0) atomicAdd(ssn + row, (u64)(q * SS_SCALE));
	v_lshlrev_b32_e32 v236, 16, v192
	v_and_b32_e32 v237, 0xffff0000, v192
	v_lshlrev_b32_e32 v238, 16, v193
	v_and_b32_e32 v239, 0xffff0000, v193
	v_lshlrev_b32_e32 v240, 16, v194
	v_and_b32_e32 v241, 0xffff0000, v194
	v_lshlrev_b32_e32 v242, 16, v195
	v_and_b32_e32 v243, 0xffff0000, v195
	v_pk_add_f32 v[56:57], v[56:57], v[236:237]
	v_pk_add_f32 v[58:59], v[58:59], v[238:239]
	v_pk_add_f32 v[60:61], v[60:61], v[240:241]
	v_pk_add_f32 v[62:63], v[62:63], v[242:243]
	v_mul_f32_e32 v236, v57, v57
	v_mul_f32_e32 v237, v59, v59
	v_mul_f32_e32 v238, v61, v61
	v_mul_f32_e32 v239, v63, v63
	v_fmac_f32_e32 v236, v56, v56
	v_fmac_f32_e32 v237, v58, v58
	v_fmac_f32_e32 v238, v60, v60
	v_fmac_f32_e32 v239, v62, v62
	v_cvt_pk_bf16_f32 v56, v56, v57
	v_cvt_pk_bf16_f32 v57, v58, v59
	v_cvt_pk_bf16_f32 v58, v60, v61
	v_cvt_pk_bf16_f32 v59, v62, v63
	v_add_f32_e32 v236, v236, v237
	v_add_f32_e32 v237, v238, v239
	v_add_f32_e32 v60, v236, v237
	v_add_u32_e32 v146, 0x80000, v159
	global_store_dwordx4 v146, v[56:59], s[28:29]
	ds_write_b128 v156, v[44:47]
	ds_write_b128 v156, v[40:43] offset:64
	ds_read_b128 v[40:43], v157
	ds_read_b128 v[44:47], v157 offset:16
	s_waitcnt vmcnt(15) lgkmcnt(4)
	v_lshlrev_b32_e32 v236, 16, v196
	v_and_b32_e32 v237, 0xffff0000, v196
	v_lshlrev_b32_e32 v238, 16, v197
	v_and_b32_e32 v239, 0xffff0000, v197
	v_lshlrev_b32_e32 v240, 16, v198
	v_and_b32_e32 v241, 0xffff0000, v198
	v_lshlrev_b32_e32 v242, 16, v199
	v_and_b32_e32 v243, 0xffff0000, v199
	v_pk_add_f32 v[48:49], v[48:49], v[236:237]
	v_pk_add_f32 v[50:51], v[50:51], v[238:239]
	v_pk_add_f32 v[52:53], v[52:53], v[240:241]
	v_pk_add_f32 v[54:55], v[54:55], v[242:243]
	v_mul_f32_e32 v236, v49, v49
	v_mul_f32_e32 v237, v51, v51
	v_mul_f32_e32 v238, v53, v53
	v_mul_f32_e32 v239, v55, v55
	v_fmac_f32_e32 v236, v48, v48
	v_fmac_f32_e32 v237, v50, v50
	v_fmac_f32_e32 v238, v52, v52
	v_fmac_f32_e32 v239, v54, v54
	v_cvt_pk_bf16_f32 v48, v48, v49
	v_cvt_pk_bf16_f32 v49, v50, v51
	v_cvt_pk_bf16_f32 v50, v52, v53
	v_cvt_pk_bf16_f32 v51, v54, v55
	v_add_f32_e32 v236, v236, v237
	v_add_f32_e32 v237, v238, v239
	v_add_f32_e32 v52, v236, v237
	global_store_dwordx4 v146, v[48:51], s[28:29] offset:64
	v_add_f32_e32 v53, v60, v52
	s_nop 1
	v_add_f32_dpp v54, v53, v53 quad_perm:[1,0,3,2] row_mask:0xf bank_mask:0xf
	s_nop 1
	v_add_f32_dpp v55, v54, v54 quad_perm:[2,3,0,1] row_mask:0xf bank_mask:0xf
	v_mul_f32_e32 v62, 0x49800000, v55
	v_trunc_f32_e32 v62, v62
	v_mul_f32_e32 v63, 0x2f800000, v62
	v_floor_f32_e32 v63, v63
	v_fmac_f32_e32 v62, 0xcf800000, v63
	v_cvt_u32_f32_e32 v62, v62
	v_cvt_u32_f32_e32 v63, v63
	ds_write_b128 v156, v[36:39]
	ds_write_b128 v156, v[32:35] offset:64
	ds_read_b128 v[32:35], v157
	ds_read_b128 v[36:39], v157 offset:16
	s_waitcnt vmcnt(15) lgkmcnt(4)
	v_lshlrev_b32_e32 v236, 16, v200
	v_and_b32_e32 v237, 0xffff0000, v200
	v_lshlrev_b32_e32 v238, 16, v201
	v_and_b32_e32 v239, 0xffff0000, v201
	v_lshlrev_b32_e32 v240, 16, v202
	v_and_b32_e32 v241, 0xffff0000, v202
	v_lshlrev_b32_e32 v242, 16, v203
	v_and_b32_e32 v243, 0xffff0000, v203
	v_pk_add_f32 v[40:41], v[40:41], v[236:237]
	v_pk_add_f32 v[42:43], v[42:43], v[238:239]
	v_pk_add_f32 v[44:45], v[44:45], v[240:241]
	v_pk_add_f32 v[46:47], v[46:47], v[242:243]
	v_mul_f32_e32 v236, v41, v41
	v_mul_f32_e32 v237, v43, v43
	v_mul_f32_e32 v238, v45, v45
	v_mul_f32_e32 v239, v47, v47
	v_fmac_f32_e32 v236, v40, v40
	v_fmac_f32_e32 v237, v42, v42
	v_fmac_f32_e32 v238, v44, v44
	v_fmac_f32_e32 v239, v46, v46
	v_cvt_pk_bf16_f32 v40, v40, v41
	v_cvt_pk_bf16_f32 v41, v42, v43
	v_cvt_pk_bf16_f32 v42, v44, v45
	v_cvt_pk_bf16_f32 v43, v46, v47
	v_add_f32_e32 v236, v236, v237
	v_add_f32_e32 v237, v238, v239
	v_add_f32_e32 v44, v236, v237
	v_add_u32_e32 v147, 0x90000, v159
	global_store_dwordx4 v147, v[40:43], s[28:29]
	ds_write_b128 v156, v[28:31]
	ds_write_b128 v156, v[24:27] offset:64
	ds_read_b128 v[24:27], v157
	ds_read_b128 v[28:31], v157 offset:16
	s_waitcnt vmcnt(15) lgkmcnt(4)
	v_lshlrev_b32_e32 v236, 16, v204
	v_and_b32_e32 v237, 0xffff0000, v204
	v_lshlrev_b32_e32 v238, 16, v205
	v_and_b32_e32 v239, 0xffff0000, v205
	v_lshlrev_b32_e32 v240, 16, v206
	v_and_b32_e32 v241, 0xffff0000, v206
	v_lshlrev_b32_e32 v242, 16, v207
	v_and_b32_e32 v243, 0xffff0000, v207
	v_pk_add_f32 v[32:33], v[32:33], v[236:237]
	v_pk_add_f32 v[34:35], v[34:35], v[238:239]
	v_pk_add_f32 v[36:37], v[36:37], v[240:241]
	v_pk_add_f32 v[38:39], v[38:39], v[242:243]
	v_mul_f32_e32 v236, v33, v33
	v_mul_f32_e32 v237, v35, v35
	v_mul_f32_e32 v238, v37, v37
	v_mul_f32_e32 v239, v39, v39
	v_fmac_f32_e32 v236, v32, v32
	v_fmac_f32_e32 v237, v34, v34
	v_fmac_f32_e32 v238, v36, v36
	v_fmac_f32_e32 v239, v38, v38
	v_cvt_pk_bf16_f32 v32, v32, v33
	v_cvt_pk_bf16_f32 v33, v34, v35
	v_cvt_pk_bf16_f32 v34, v36, v37
	v_cvt_pk_bf16_f32 v35, v38, v39
	v_add_f32_e32 v236, v236, v237
	v_add_f32_e32 v237, v238, v239
	v_add_f32_e32 v36, v236, v237
	global_store_dwordx4 v147, v[32:35], s[28:29] offset:64
	v_add_f32_e32 v37, v44, v36
	s_nop 1
	v_add_f32_dpp v38, v37, v37 quad_perm:[1,0,3,2] row_mask:0xf bank_mask:0xf
	s_nop 1
	v_add_f32_dpp v39, v38, v38 quad_perm:[2,3,0,1] row_mask:0xf bank_mask:0xf
	v_mul_f32_e32 v46, 0x49800000, v39
	v_trunc_f32_e32 v46, v46
	v_mul_f32_e32 v47, 0x2f800000, v46
	v_floor_f32_e32 v47, v47
	v_fmac_f32_e32 v46, 0xcf800000, v47
	v_cvt_u32_f32_e32 v46, v46
	v_cvt_u32_f32_e32 v47, v47
	ds_write_b128 v156, v[20:23]
	ds_write_b128 v156, v[16:19] offset:64
	ds_read_b128 v[16:19], v157
	ds_read_b128 v[20:23], v157 offset:16
	s_waitcnt vmcnt(15) lgkmcnt(4)
; #define PG8_LAS __attribute__((address_space(3)))
; __device__ __forceinline__ unsigned cvt_pk_bf16(float lo, float hi) { unsigned r; asm volatile("v_cvt_pk_bf16_f32 %0, %1, %2" : "=v"(r) : "v"(lo), "v"(hi)); return r; }
;     __device__ __forceinline__ void operator()(const f32x4 (&acc)[2][2][4][2], const Unit& u, int wr, int wc, int fr, int fq) const {
;     ...
;                 for (int bj = 0; bj < 2; ++bj) {
;                     const size_t off = (size_t)row * 2048 + u.pn * BM + wc * 64 + bj * 32 + 8 * p;
;                     f32x4 b0, b1;
;                     if (BASE_F32) { b0 = *(const f32x4*)((const float*)base + off); b1 = *(const f32x4*)((const float*)base + off + 4); }
;                     else { const u32x4 bb = *(const u32x4*)((const bf16_t*)base + off);
;                         b0 = (f32x4){__uint_as_float(bb.x << 16), __uint_as_float(bb.x & 0xffff0000u), __uint_as_float(bb.y << 16), __uint_as_float(bb.y & 0xffff0000u)};
;                         b1 = (f32x4){__uint_as_float(bb.z << 16), __uint_as_float(bb.z & 0xffff0000u), __uint_as_float(bb.w << 16), __uint_as_float(bb.w & 0xffff0000u)}; }
; #pragma unroll
;                     for (int n = 0; n < 2; ++n) *(PG8_LAS f32x4*)(stg + fr * STG_ROW + n * 64 + fq * 16) = acc[ai][bj][m][n];
;                     const f32x4 v0 = *(const PG8_LAS f32x4*)(stg + r * STG_ROW + p * 32) + b0, v1 = *(const PG8_LAS f32x4*)(stg + r * STG_ROW + p * 32 + 16) + b1;
;                     q += ((v0[0] * v0[0] + v0[1] * v0[1]) + (v0[2] * v0[2] + v0[3] * v0[3])) + ((v1[0] * v1[0] + v1[1] * v1[1]) + (v1[2] * v1[2] + v1[3] * v1[3]));
;                     u32x4 w; w.x = cvt_pk_bf16(v0[0], v0[1]); w.y = cvt_pk_bf16(v0[2], v0[3]); w.z = cvt_pk_bf16(v1[0], v1[1]); w.w = cvt_pk_bf16(v1[2], v1[3]);
;                     *(u32x4*)(out + off) = w;
;                 }
;                 q += __shfl_xor(q, 1); q += __shfl_xor(q, 2);
;                 if (p == 0) atomicAdd(ssn + row, (u64)(q * SS_SCALE));
	v_lshlrev_b32_e32 v236, 16, v212
	v_and_b32_e32 v237, 0xffff0000, v212
	v_lshlrev_b32_e32 v238, 16, v213
	v_and_b32_e32 v239, 0xffff0000, v213
	v_lshlrev_b32_e32 v240, 16, v214
	v_and_b32_e32 v241, 0xffff0000, v214
	v_lshlrev_b32_e32 v242, 16, v215
	v_and_b32_e32 v243, 0xffff0000, v215
	v_pk_add_f32 v[24:25], v[24:25], v[236:237]
	v_pk_add_f32 v[26:27], v[26:27], v[238:239]
	v_pk_add_f32 v[28:29], v[28:29], v[240:241]
	v_pk_add_f32 v[30:31], v[30:31], v[242:243]
	v_mul_f32_e32 v236, v25, v25
	v_mul_f32_e32 v237, v27, v27
	v_mul_f32_e32 v238, v29, v29
	v_mul_f32_e32 v239, v31, v31
	v_fmac_f32_e32 v236, v24, v24
	v_fmac_f32_e32 v237, v26, v26
	v_fmac_f32_e32 v238, v28, v28
	v_fmac_f32_e32 v239, v30, v30
	v_cvt_pk_bf16_f32 v24, v24, v25
	v_cvt_pk_bf16_f32 v25, v26, v27
	v_cvt_pk_bf16_f32 v26, v28, v29
	v_cvt_pk_bf16_f32 v27, v30, v31
	v_add_f32_e32 v236, v236, v237
	v_add_f32_e32 v237, v238, v239
	v_add_f32_e32 v28, v236, v237
	v_add_u32_e32 v146, 0xa0000, v159
	global_store_dwordx4 v146, v[24:27], s[28:29]
	ds_write_b128 v156, v[12:15]
	ds_write_b128 v156, v[8:11] offset:64
	ds_read_b128 v[8:11], v157
	ds_read_b128 v[12:15], v157 offset:16
	s_waitcnt vmcnt(15) lgkmcnt(4)
	v_lshlrev_b32_e32 v236, 16, v216
	v_and_b32_e32 v237, 0xffff0000, v216
	v_lshlrev_b32_e32 v238, 16, v217
	v_and_b32_e32 v239, 0xffff0000, v217
	v_lshlrev_b32_e32 v240, 16, v218
	v_and_b32_e32 v241, 0xffff0000, v218
	v_lshlrev_b32_e32 v242, 16, v219
	v_and_b32_e32 v243, 0xffff0000, v219
	v_pk_add_f32 v[16:17], v[16:17], v[236:237]
	v_pk_add_f32 v[18:19], v[18:19], v[238:239]
	v_pk_add_f32 v[20:21], v[20:21], v[240:241]
	v_pk_add_f32 v[22:23], v[22:23], v[242:243]
	v_mul_f32_e32 v236, v17, v17
	v_mul_f32_e32 v237, v19, v19
	v_mul_f32_e32 v238, v21, v21
	v_mul_f32_e32 v239, v23, v23
	v_fmac_f32_e32 v236, v16, v16
	v_fmac_f32_e32 v237, v18, v18
	v_fmac_f32_e32 v238, v20, v20
	v_fmac_f32_e32 v239, v22, v22
	v_cvt_pk_bf16_f32 v16, v16, v17
	v_cvt_pk_bf16_f32 v17, v18, v19
	v_cvt_pk_bf16_f32 v18, v20, v21
	v_cvt_pk_bf16_f32 v19, v22, v23
	v_add_f32_e32 v236, v236, v237
	v_add_f32_e32 v237, v238, v239
	v_add_f32_e32 v20, v236, v237
	global_store_dwordx4 v146, v[16:19], s[28:29] offset:64
	v_add_f32_e32 v21, v28, v20
	s_nop 1
	v_add_f32_dpp v22, v21, v21 quad_perm:[1,0,3,2] row_mask:0xf bank_mask:0xf
	s_nop 1
	v_add_f32_dpp v23, v22, v22 quad_perm:[2,3,0,1] row_mask:0xf bank_mask:0xf
	v_mul_f32_e32 v30, 0x49800000, v23
	v_trunc_f32_e32 v30, v30
	v_mul_f32_e32 v31, 0x2f800000, v30
	v_floor_f32_e32 v31, v31
	v_fmac_f32_e32 v30, 0xcf800000, v31
	v_cvt_u32_f32_e32 v30, v30
	v_cvt_u32_f32_e32 v31, v31
	ds_write_b128 v156, v[4:7]
	ds_write_b128 v156, v[0:3] offset:64
	ds_read_b128 v[0:3], v157
	ds_read_b128 v[4:7], v157 offset:16
	s_waitcnt vmcnt(15) lgkmcnt(4)
	v_lshlrev_b32_e32 v236, 16, v220
	v_and_b32_e32 v237, 0xffff0000, v220
	v_lshlrev_b32_e32 v238, 16, v221
	v_and_b32_e32 v239, 0xffff0000, v221
	v_lshlrev_b32_e32 v240, 16, v222
	v_and_b32_e32 v241, 0xffff0000, v222
	v_lshlrev_b32_e32 v242, 16, v223
	v_and_b32_e32 v243, 0xffff0000, v223
	v_pk_add_f32 v[8:9], v[8:9], v[236:237]
	v_pk_add_f32 v[10:11], v[10:11], v[238:239]
	v_pk_add_f32 v[12:13], v[12:13], v[240:241]
	v_pk_add_f32 v[14:15], v[14:15], v[242:243]
	v_mul_f32_e32 v236, v9, v9
	v_mul_f32_e32 v237, v11, v11
	v_mul_f32_e32 v238, v13, v13
	v_mul_f32_e32 v239, v15, v15
	v_fmac_f32_e32 v236, v8, v8
	v_fmac_f32_e32 v237, v10, v10
	v_fmac_f32_e32 v238, v12, v12
	v_fmac_f32_e32 v239, v14, v14
	v_cvt_pk_bf16_f32 v8, v8, v9
	v_cvt_pk_bf16_f32 v9, v10, v11
	v_cvt_pk_bf16_f32 v10, v12, v13
	v_cvt_pk_bf16_f32 v11, v14, v15
	v_add_f32_e32 v236, v236, v237
	v_add_f32_e32 v237, v238, v239
	v_add_f32_e32 v12, v236, v237
	v_add_u32_e32 v147, 0xb0000, v159
	global_store_dwordx4 v147, v[8:11], s[28:29]
	s_waitcnt vmcnt(15) lgkmcnt(0)
	v_lshlrev_b32_e32 v236, 16, v224
	v_and_b32_e32 v237, 0xffff0000, v224
	v_lshlrev_b32_e32 v238, 16, v225
	v_and_b32_e32 v239, 0xffff0000, v225
	v_lshlrev_b32_e32 v240, 16, v226
	v_and_b32_e32 v241, 0xffff0000, v226
	v_lshlrev_b32_e32 v242, 16, v227
	v_and_b32_e32 v243, 0xffff0000, v227
	v_pk_add_f32 v[0:1], v[0:1], v[236:237]
	v_pk_add_f32 v[2:3], v[2:3], v[238:239]
	v_pk_add_f32 v[4:5], v[4:5], v[240:241]
	v_pk_add_f32 v[6:7], v[6:7], v[242:243]
	v_mul_f32_e32 v236, v1, v1
	v_mul_f32_e32 v237, v3, v3
	v_mul_f32_e32 v238, v5, v5
	v_mul_f32_e32 v239, v7, v7
	v_fmac_f32_e32 v236, v0, v0
	v_fmac_f32_e32 v237, v2, v2
	v_fmac_f32_e32 v238, v4, v4
	v_fmac_f32_e32 v239, v6, v6
	v_cvt_pk_bf16_f32 v0, v0, v1
	v_cvt_pk_bf16_f32 v1, v2, v3
	v_cvt_pk_bf16_f32 v2, v4, v5
	v_cvt_pk_bf16_f32 v3, v6, v7
	v_add_f32_e32 v236, v236, v237
	v_add_f32_e32 v237, v238, v239
	v_add_f32_e32 v4, v236, v237
	global_store_dwordx4 v147, v[0:3], s[28:29] offset:64
	v_add_f32_e32 v5, v12, v4
	s_nop 1
	v_add_f32_dpp v6, v5, v5 quad_perm:[1,0,3,2] row_mask:0xf bank_mask:0xf
	s_nop 1
	v_add_f32_dpp v7, v6, v6 quad_perm:[2,3,0,1] row_mask:0xf bank_mask:0xf
	v_mul_f32_e32 v14, 0x49800000, v7
	v_trunc_f32_e32 v14, v14
	v_mul_f32_e32 v15, 0x2f800000, v14
	v_floor_f32_e32 v15, v15
	v_fmac_f32_e32 v14, 0xcf800000, v15
	v_cvt_u32_f32_e32 v14, v14
	v_cvt_u32_f32_e32 v15, v15
	v_and_b32_e32 v236, 3, v252
	v_lshl_add_u32 v237, v236, 7, v208
	v_cmp_eq_u32_e64 s[100:101], 1, v236
	v_cndmask_b32_e64 v126, v126, v110, s[100:101]
	v_cndmask_b32_e64 v127, v127, v111, s[100:101]
	v_cmp_eq_u32_e64 s[100:101], 2, v236
	v_cndmask_b32_e64 v126, v126, v94, s[100:101]
	v_cndmask_b32_e64 v127, v127, v95, s[100:101]
	v_cmp_eq_u32_e64 s[100:101], 3, v236
	v_cndmask_b32_e64 v126, v126, v78, s[100:101]
	v_cndmask_b32_e64 v127, v127, v79, s[100:101]
	global_atomic_add_x2 v237, v[126:127], s[12:13]
	v_cmp_eq_u32_e64 s[100:101], 1, v236
	v_cndmask_b32_e64 v62, v62, v46, s[100:101]
	v_cndmask_b32_e64 v63, v63, v47, s[100:101]
	v_cmp_eq_u32_e64 s[100:101], 2, v236
	v_cndmask_b32_e64 v62, v62, v30, s[100:101]
	v_cndmask_b32_e64 v63, v63, v31, s[100:101]
	v_cmp_eq_u32_e64 s[100:101], 3, v236
	v_cndmask_b32_e64 v62, v62, v14, s[100:101]
	v_cndmask_b32_e64 v63, v63, v15, s[100:101]
	global_atomic_add_x2 v237, v[62:63], s[12:13] offset:1024
	s_andn2_b64 vcc, exec, s[10:11]
	s_mov_b64 s[10:11], -1
	s_cbranch_vccnz .LBB0_759
	s_andn2_b64 vcc, exec, s[44:45]
	s_cbranch_vccnz .LBB0_758
	s_mov_b32 s98, 1
	s_branch .LBB0_758

; #define PG8_LAS __attribute__((address_space(3)))
; __device__ __forceinline__ unsigned cvt_pk_bf16(float lo, float hi) { unsigned r; asm volatile("v_cvt_pk_bf16_f32 %0, %1, %2" : "=v"(r) : "v"(lo), "v"(hi)); return r; }
;     __device__ __forceinline__ void operator()(const f32x4 (&acc)[2][2][4][2], const Unit& u, int wr, int wc, int fr, int fq) const {
;     ...
;                 for (int bj = 0; bj < 2; ++bj) {
;                     const size_t off = (size_t)row * 2048 + u.pn * BM + wc * 64 + bj * 32 + 8 * p;
;                     f32x4 b0, b1;
;                     if (BASE_F32) { b0 = *(const f32x4*)((const float*)base + off); b1 = *(const f32x4*)((const float*)base + off + 4); }
;                     else { const u32x4 bb = *(const u32x4*)((const bf16_t*)base + off);
;                         b0 = (f32x4){__uint_as_float(bb.x << 16), __uint_as_float(bb.x & 0xffff0000u), __uint_as_float(bb.y << 16), __uint_as_float(bb.y & 0xffff0000u)};
;                         b1 = (f32x4){__uint_as_float(bb.z << 16), __uint_as_float(bb.z & 0xffff0000u), __uint_as_float(bb.w << 16), __uint_as_float(bb.w & 0xffff0000u)}; }
; #pragma unroll
;                     for (int n = 0; n < 2; ++n) *(PG8_LAS f32x4*)(stg + fr * STG_ROW + n * 64 + fq * 16) = acc[ai][bj][m][n];
;                     const f32x4 v0 = *(const PG8_LAS f32x4*)(stg + r * STG_ROW + p * 32) + b0, v1 = *(const PG8_LAS f32x4*)(stg + r * STG_ROW + p * 32 + 16) + b1;
;                     q += ((v0[0] * v0[0] + v0[1] * v0[1]) + (v0[2] * v0[2] + v0[3] * v0[3])) + ((v1[0] * v1[0] + v1[1] * v1[1]) + (v1[2] * v1[2] + v1[3] * v1[3]));
;                     u32x4 w; w.x = cvt_pk_bf16(v0[0], v0[1]); w.y = cvt_pk_bf16(v0[2], v0[3]); w.z = cvt_pk_bf16(v1[0], v1[1]); w.w = cvt_pk_bf16(v1[2], v1[3]);
;                     *(u32x4*)(out + off) = w;
;                 }
;                 q += __shfl_xor(q, 1); q += __shfl_xor(q, 2);
;                 if (p == 0) atomicAdd(ssn + row, (u64)(q * SS_SCALE));
.LBB0_952:
	ds_write_b128 v156, v[124:127]
	ds_write_b128 v156, v[120:123] offset:64
	ds_read_b128 v[120:123], v157
	ds_read_b128 v[124:127], v157 offset:16
	ds_write_b128 v156, v[116:119]
	ds_write_b128 v156, v[112:115] offset:64
	ds_read_b128 v[112:115], v157
	ds_read_b128 v[116:119], v157 offset:16
	s_waitcnt vmcnt(15) lgkmcnt(4)
	v_lshlrev_b32_e32 v236, 16, v160
	v_and_b32_e32 v237, 0xffff0000, v160
	v_lshlrev_b32_e32 v238, 16, v161
	v_and_b32_e32 v239, 0xffff0000, v161
	v_lshlrev_b32_e32 v240, 16, v162
	v_and_b32_e32 v241, 0xffff0000, v162
	v_lshlrev_b32_e32 v242, 16, v163
	v_and_b32_e32 v243, 0xffff0000, v163
	v_pk_add_f32 v[120:121], v[120:121], v[236:237]
	v_pk_add_f32 v[122:123], v[122:123], v[238:239]
	v_pk_add_f32 v[124:125], v[124:125], v[240:241]
	v_pk_add_f32 v[126:127], v[126:127], v[242:243]
	v_mul_f32_e32 v236, v121, v121
	v_mul_f32_e32 v237, v123, v123
	v_mul_f32_e32 v238, v125, v125
	v_mul_f32_e32 v239, v127, v127
	v_fmac_f32_e32 v236, v120, v120
	v_fmac_f32_e32 v237, v122, v122
	v_fmac_f32_e32 v238, v124, v124
	v_fmac_f32_e32 v239, v126, v126
	v_cvt_pk_bf16_f32 v120, v120, v121
	v_cvt_pk_bf16_f32 v121, v122, v123
	v_cvt_pk_bf16_f32 v122, v124, v125
	v_cvt_pk_bf16_f32 v123, v126, v127
	v_add_f32_e32 v236, v236, v237
	v_add_f32_e32 v237, v238, v239
	v_add_f32_e32 v124, v236, v237
	global_store_dwordx4 v159, v[120:123], s[28:29]
	ds_write_b128 v156, v[108:111]
	ds_write_b128 v156, v[104:107] offset:64
	ds_read_b128 v[104:107], v157
	ds_read_b128 v[108:111], v157 offset:16
	s_waitcnt vmcnt(15) lgkmcnt(4)
	v_lshlrev_b32_e32 v236, 16, v164
	v_and_b32_e32 v237, 0xffff0000, v164
	v_lshlrev_b32_e32 v238, 16, v165
	v_and_b32_e32 v239, 0xffff0000, v165
	v_lshlrev_b32_e32 v240, 16, v166
	v_and_b32_e32 v241, 0xffff0000, v166
	v_lshlrev_b32_e32 v242, 16, v167
	v_and_b32_e32 v243, 0xffff0000, v167
	v_pk_add_f32 v[112:113], v[112:113], v[236:237]
	v_pk_add_f32 v[114:115], v[114:115], v[238:239]
	v_pk_add_f32 v[116:117], v[116:117], v[240:241]
	v_pk_add_f32 v[118:119], v[118:119], v[242:243]
	v_mul_f32_e32 v236, v113, v113
	v_mul_f32_e32 v237, v115, v115
	v_mul_f32_e32 v238, v117, v117
	v_mul_f32_e32 v239, v119, v119
	v_fmac_f32_e32 v236, v112, v112
	v_fmac_f32_e32 v237, v114, v114
	v_fmac_f32_e32 v238, v116, v116
	v_fmac_f32_e32 v239, v118, v118
	v_cvt_pk_bf16_f32 v112, v112, v113
	v_cvt_pk_bf16_f32 v113, v114, v115
	v_cvt_pk_bf16_f32 v114, v116, v117
	v_cvt_pk_bf16_f32 v115, v118, v119
	v_add_f32_e32 v236, v236, v237
	v_add_f32_e32 v237, v238, v239
	v_add_f32_e32 v116, v236, v237
	global_store_dwordx4 v159, v[112:115], s[28:29] offset:64
	v_add_f32_e32 v117, v124, v116
	s_nop 1
	v_add_f32_dpp v118, v117, v117 quad_perm:[1,0,3,2] row_mask:0xf bank_mask:0xf
	s_nop 1
	v_add_f32_dpp v119, v118, v118 quad_perm:[2,3,0,1] row_mask:0xf bank_mask:0xf
	v_mul_f32_e32 v126, 0x49800000, v119
	v_trunc_f32_e32 v126, v126
	v_mul_f32_e32 v127, 0x2f800000, v126
	v_floor_f32_e32 v127, v127
	v_fmac_f32_e32 v126, 0xcf800000, v127
	v_cvt_u32_f32_e32 v126, v126
	v_cvt_u32_f32_e32 v127, v127
	ds_write_b128 v156, v[100:103]
	ds_write_b128 v156, v[96:99] offset:64
	ds_read_b128 v[96:99], v157
	ds_read_b128 v[100:103], v157 offset:16
	s_waitcnt vmcnt(15) lgkmcnt(4)
	v_lshlrev_b32_e32 v236, 16, v168
	v_and_b32_e32 v237, 0xffff0000, v168
	v_lshlrev_b32_e32 v238, 16, v169
	v_and_b32_e32 v239, 0xffff0000, v169
	v_lshlrev_b32_e32 v240, 16, v170
	v_and_b32_e32 v241, 0xffff0000, v170
	v_lshlrev_b32_e32 v242, 16, v171
	v_and_b32_e32 v243, 0xffff0000, v171
	v_pk_add_f32 v[104:105], v[104:105], v[236:237]
	v_pk_add_f32 v[106:107], v[106:107], v[238:239]
	v_pk_add_f32 v[108:109], v[108:109], v[240:241]
	v_pk_add_f32 v[110:111], v[110:111], v[242:243]
	v_mul_f32_e32 v236, v105, v105
	v_mul_f32_e32 v237, v107, v107
	v_mul_f32_e32 v238, v109, v109
	v_mul_f32_e32 v239, v111, v111
	v_fmac_f32_e32 v236, v104, v104
	v_fmac_f32_e32 v237, v106, v106
	v_fmac_f32_e32 v238, v108, v108
	v_fmac_f32_e32 v239, v110, v110
	v_cvt_pk_bf16_f32 v104, v104, v105
	v_cvt_pk_bf16_f32 v105, v106, v107
	v_cvt_pk_bf16_f32 v106, v108, v109
	v_cvt_pk_bf16_f32 v107, v110, v111
	v_add_f32_e32 v236, v236, v237
	v_add_f32_e32 v237, v238, v239
	v_add_f32_e32 v108, v236, v237
	v_add_u32_e32 v147, 0x10000, v159
	global_store_dwordx4 v147, v[104:107], s[28:29]
	ds_write_b128 v156, v[92:95]
	ds_write_b128 v156, v[88:91] offset:64
	ds_read_b128 v[88:91], v157
	ds_read_b128 v[92:95], v157 offset:16
	s_waitcnt vmcnt(15) lgkmcnt(4)
	v_lshlrev_b32_e32 v236, 16, v172
	v_and_b32_e32 v237, 0xffff0000, v172
	v_lshlrev_b32_e32 v238, 16, v173
	v_and_b32_e32 v239, 0xffff0000, v173
	v_lshlrev_b32_e32 v240, 16, v174
	v_and_b32_e32 v241, 0xffff0000, v174
	v_lshlrev_b32_e32 v242, 16, v175
	v_and_b32_e32 v243, 0xffff0000, v175
	v_pk_add_f32 v[96:97], v[96:97], v[236:237]
	v_pk_add_f32 v[98:99], v[98:99], v[238:239]
	v_pk_add_f32 v[100:101], v[100:101], v[240:241]
	v_pk_add_f32 v[102:103], v[102:103], v[242:243]
	v_mul_f32_e32 v236, v97, v97
	v_mul_f32_e32 v237, v99, v99
	v_mul_f32_e32 v238, v101, v101
	v_mul_f32_e32 v239, v103, v103
	v_fmac_f32_e32 v236, v96, v96
	v_fmac_f32_e32 v237, v98, v98
	v_fmac_f32_e32 v238, v100, v100
	v_fmac_f32_e32 v239, v102, v102
	v_cvt_pk_bf16_f32 v96, v96, v97
	v_cvt_pk_bf16_f32 v97, v98, v99
	v_cvt_pk_bf16_f32 v98, v100, v101
	v_cvt_pk_bf16_f32 v99, v102, v103
	v_add_f32_e32 v236, v236, v237
	v_add_f32_e32 v237, v238, v239
	v_add_f32_e32 v100, v236, v237
	global_store_dwordx4 v147, v[96:99], s[28:29] offset:64
	v_add_f32_e32 v101, v108, v100
	s_nop 1
	v_add_f32_dpp v102, v101, v101 quad_perm:[1,0,3,2] row_mask:0xf bank_mask:0xf
	s_nop 1
	v_add_f32_dpp v103, v102, v102 quad_perm:[2,3,0,1] row_mask:0xf bank_mask:0xf
	v_mul_f32_e32 v110, 0x49800000, v103
	v_trunc_f32_e32 v110, v110
	v_mul_f32_e32 v111, 0x2f800000, v110
	v_floor_f32_e32 v111, v111
	v_fmac_f32_e32 v110, 0xcf800000, v111
	v_cvt_u32_f32_e32 v110, v110
	v_cvt_u32_f32_e32 v111, v111
	ds_write_b128 v156, v[84:87]
	ds_write_b128 v156, v[80:83] offset:64
	ds_read_b128 v[80:83], v157
	ds_read_b128 v[84:87], v157 offset:16
	s_waitcnt vmcnt(15) lgkmcnt(4)
; #define PG8_LAS __attribute__((address_space(3)))
; __device__ __forceinline__ unsigned cvt_pk_bf16(float lo, float hi) { unsigned r; asm volatile("v_cvt_pk_bf16_f32 %0, %1, %2" : "=v"(r) : "v"(lo), "v"(hi)); return r; }
;     __device__ __forceinline__ void operator()(const f32x4 (&acc)[2][2][4][2], const Unit& u, int wr, int wc, int fr, int fq) const {
;     ...
;                 for (int bj = 0; bj < 2; ++bj) {
;                     const size_t off = (size_t)row * 2048 + u.pn * BM + wc * 64 + bj * 32 + 8 * p;
;                     f32x4 b0, b1;
;                     if (BASE_F32) { b0 = *(const f32x4*)((const float*)base + off); b1 = *(const f32x4*)((const float*)base + off + 4); }
;                     else { const u32x4 bb = *(const u32x4*)((const bf16_t*)base + off);
;                         b0 = (f32x4){__uint_as_float(bb.x << 16), __uint_as_float(bb.x & 0xffff0000u), __uint_as_float(bb.y << 16), __uint_as_float(bb.y & 0xffff0000u)};
;                         b1 = (f32x4){__uint_as_float(bb.z << 16), __uint_as_float(bb.z & 0xffff0000u), __uint_as_float(bb.w << 16), __uint_as_float(bb.w & 0xffff0000u)}; }
; #pragma unroll
;                     for (int n = 0; n < 2; ++n) *(PG8_LAS f32x4*)(stg + fr * STG_ROW + n * 64 + fq * 16) = acc[ai][bj][m][n];
;                     const f32x4 v0 = *(const PG8_LAS f32x4*)(stg + r * STG_ROW + p * 32) + b0, v1 = *(const PG8_LAS f32x4*)(stg + r * STG_ROW + p * 32 + 16) + b1;
;                     q += ((v0[0] * v0[0] + v0[1] * v0[1]) + (v0[2] * v0[2] + v0[3] * v0[3])) + ((v1[0] * v1[0] + v1[1] * v1[1]) + (v1[2] * v1[2] + v1[3] * v1[3]));
;                     u32x4 w; w.x = cvt_pk_bf16(v0[0], v0[1]); w.y = cvt_pk_bf16(v0[2], v0[3]); w.z = cvt_pk_bf16(v1[0], v1[1]); w.w = cvt_pk_bf16(v1[2], v1[3]);
;                     *(u32x4*)(out + off) = w;
;                 }
;                 q += __shfl_xor(q, 1); q += __shfl_xor(q, 2);
;                 if (p == 0) atomicAdd(ssn + row, (u64)(q * SS_SCALE));
	v_lshlrev_b32_e32 v236, 16, v176
	v_and_b32_e32 v237, 0xffff0000, v176
	v_lshlrev_b32_e32 v238, 16, v177
	v_and_b32_e32 v239, 0xffff0000, v177
	v_lshlrev_b32_e32 v240, 16, v178
	v_and_b32_e32 v241, 0xffff0000, v178
	v_lshlrev_b32_e32 v242, 16, v179
	v_and_b32_e32 v243, 0xffff0000, v179
	v_pk_add_f32 v[88:89], v[88:89], v[236:237]
	v_pk_add_f32 v[90:91], v[90:91], v[238:239]
	v_pk_add_f32 v[92:93], v[92:93], v[240:241]
	v_pk_add_f32 v[94:95], v[94:95], v[242:243]
	v_mul_f32_e32 v236, v89, v89
	v_mul_f32_e32 v237, v91, v91
	v_mul_f32_e32 v238, v93, v93
	v_mul_f32_e32 v239, v95, v95
	v_fmac_f32_e32 v236, v88, v88
	v_fmac_f32_e32 v237, v90, v90
	v_fmac_f32_e32 v238, v92, v92
	v_fmac_f32_e32 v239, v94, v94
	v_cvt_pk_bf16_f32 v88, v88, v89
	v_cvt_pk_bf16_f32 v89, v90, v91
	v_cvt_pk_bf16_f32 v90, v92, v93
	v_cvt_pk_bf16_f32 v91, v94, v95
	v_add_f32_e32 v236, v236, v237
	v_add_f32_e32 v237, v238, v239
	v_add_f32_e32 v92, v236, v237
	v_add_u32_e32 v146, 0x20000, v159
	global_store_dwordx4 v146, v[88:91], s[28:29]
	ds_write_b128 v156, v[76:79]
	ds_write_b128 v156, v[72:75] offset:64
	ds_read_b128 v[72:75], v157
	ds_read_b128 v[76:79], v157 offset:16
	s_waitcnt vmcnt(15) lgkmcnt(4)
	v_lshlrev_b32_e32 v236, 16, v180
	v_and_b32_e32 v237, 0xffff0000, v180
	v_lshlrev_b32_e32 v238, 16, v181
	v_and_b32_e32 v239, 0xffff0000, v181
	v_lshlrev_b32_e32 v240, 16, v182
	v_and_b32_e32 v241, 0xffff0000, v182
	v_lshlrev_b32_e32 v242, 16, v183
	v_and_b32_e32 v243, 0xffff0000, v183
	v_pk_add_f32 v[80:81], v[80:81], v[236:237]
	v_pk_add_f32 v[82:83], v[82:83], v[238:239]
	v_pk_add_f32 v[84:85], v[84:85], v[240:241]
	v_pk_add_f32 v[86:87], v[86:87], v[242:243]
	v_mul_f32_e32 v236, v81, v81
	v_mul_f32_e32 v237, v83, v83
	v_mul_f32_e32 v238, v85, v85
	v_mul_f32_e32 v239, v87, v87
	v_fmac_f32_e32 v236, v80, v80
	v_fmac_f32_e32 v237, v82, v82
	v_fmac_f32_e32 v238, v84, v84
	v_fmac_f32_e32 v239, v86, v86
	v_cvt_pk_bf16_f32 v80, v80, v81
	v_cvt_pk_bf16_f32 v81, v82, v83
	v_cvt_pk_bf16_f32 v82, v84, v85
	v_cvt_pk_bf16_f32 v83, v86, v87
	v_add_f32_e32 v236, v236, v237
	v_add_f32_e32 v237, v238, v239
	v_add_f32_e32 v84, v236, v237
	global_store_dwordx4 v146, v[80:83], s[28:29] offset:64
	v_add_f32_e32 v85, v92, v84
	s_nop 1
	v_add_f32_dpp v86, v85, v85 quad_perm:[1,0,3,2] row_mask:0xf bank_mask:0xf
	s_nop 1
	v_add_f32_dpp v87, v86, v86 quad_perm:[2,3,0,1] row_mask:0xf bank_mask:0xf
	v_mul_f32_e32 v94, 0x49800000, v87
	v_trunc_f32_e32 v94, v94
	v_mul_f32_e32 v95, 0x2f800000, v94
	v_floor_f32_e32 v95, v95
	v_fmac_f32_e32 v94, 0xcf800000, v95
	v_cvt_u32_f32_e32 v94, v94
	v_cvt_u32_f32_e32 v95, v95
	ds_write_b128 v156, v[68:71]
	ds_write_b128 v156, v[64:67] offset:64
	ds_read_b128 v[64:67], v157
	ds_read_b128 v[68:71], v157 offset:16
	s_waitcnt vmcnt(15) lgkmcnt(4)
	v_lshlrev_b32_e32 v236, 16, v184
	v_and_b32_e32 v237, 0xffff0000, v184
	v_lshlrev_b32_e32 v238, 16, v185
	v_and_b32_e32 v239, 0xffff0000, v185
	v_lshlrev_b32_e32 v240, 16, v186
	v_and_b32_e32 v241, 0xffff0000, v186
	v_lshlrev_b32_e32 v242, 16, v187
	v_and_b32_e32 v243, 0xffff0000, v187
	v_pk_add_f32 v[72:73], v[72:73], v[236:237]
	v_pk_add_f32 v[74:75], v[74:75], v[238:239]
	v_pk_add_f32 v[76:77], v[76:77], v[240:241]
	v_pk_add_f32 v[78:79], v[78:79], v[242:243]
	v_mul_f32_e32 v236, v73, v73
	v_mul_f32_e32 v237, v75, v75
	v_mul_f32_e32 v238, v77, v77
	v_mul_f32_e32 v239, v79, v79
	v_fmac_f32_e32 v236, v72, v72
	v_fmac_f32_e32 v237, v74, v74
	v_fmac_f32_e32 v238, v76, v76
	v_fmac_f32_e32 v239, v78, v78
	v_cvt_pk_bf16_f32 v72, v72, v73
	v_cvt_pk_bf16_f32 v73, v74, v75
	v_cvt_pk_bf16_f32 v74, v76, v77
	v_cvt_pk_bf16_f32 v75, v78, v79
	v_add_f32_e32 v236, v236, v237
	v_add_f32_e32 v237, v238, v239
	v_add_f32_e32 v76, v236, v237
	v_add_u32_e32 v147, 0x30000, v159
	global_store_dwordx4 v147, v[72:75], s[28:29]
	ds_write_b128 v156, v[60:63]
	ds_write_b128 v156, v[56:59] offset:64
	ds_read_b128 v[56:59], v157
	ds_read_b128 v[60:63], v157 offset:16
	s_waitcnt vmcnt(15) lgkmcnt(4)
	v_lshlrev_b32_e32 v236, 16, v188
	v_and_b32_e32 v237, 0xffff0000, v188
	v_lshlrev_b32_e32 v238, 16, v189
	v_and_b32_e32 v239, 0xffff0000, v189
	v_lshlrev_b32_e32 v240, 16, v190
	v_and_b32_e32 v241, 0xffff0000, v190
	v_lshlrev_b32_e32 v242, 16, v191
	v_and_b32_e32 v243, 0xffff0000, v191
	v_pk_add_f32 v[64:65], v[64:65], v[236:237]
	v_pk_add_f32 v[66:67], v[66:67], v[238:239]
	v_pk_add_f32 v[68:69], v[68:69], v[240:241]
	v_pk_add_f32 v[70:71], v[70:71], v[242:243]
	v_mul_f32_e32 v236, v65, v65
	v_mul_f32_e32 v237, v67, v67
	v_mul_f32_e32 v238, v69, v69
	v_mul_f32_e32 v239, v71, v71
	v_fmac_f32_e32 v236, v64, v64
	v_fmac_f32_e32 v237, v66, v66
	v_fmac_f32_e32 v238, v68, v68
	v_fmac_f32_e32 v239, v70, v70
	v_cvt_pk_bf16_f32 v64, v64, v65
	v_cvt_pk_bf16_f32 v65, v66, v67
	v_cvt_pk_bf16_f32 v66, v68, v69
	v_cvt_pk_bf16_f32 v67, v70, v71
	v_add_f32_e32 v236, v236, v237
	v_add_f32_e32 v237, v238, v239
	v_add_f32_e32 v68, v236, v237
	global_store_dwordx4 v147, v[64:67], s[28:29] offset:64
	v_add_f32_e32 v69, v76, v68
	s_nop 1
	v_add_f32_dpp v70, v69, v69 quad_perm:[1,0,3,2] row_mask:0xf bank_mask:0xf
	s_nop 1
	v_add_f32_dpp v71, v70, v70 quad_perm:[2,3,0,1] row_mask:0xf bank_mask:0xf
	v_mul_f32_e32 v78, 0x49800000, v71
	v_trunc_f32_e32 v78, v78
	v_mul_f32_e32 v79, 0x2f800000, v78
	v_floor_f32_e32 v79, v79
	v_fmac_f32_e32 v78, 0xcf800000, v79
	v_cvt_u32_f32_e32 v78, v78
	v_cvt_u32_f32_e32 v79, v79
	ds_write_b128 v156, v[52:55]
	ds_write_b128 v156, v[48:51] offset:64
	ds_read_b128 v[48:51], v157
	ds_read_b128 v[52:55], v157 offset:16
	s_waitcnt vmcnt(15) lgkmcnt(4)
; #define PG8_LAS __attribute__((address_space(3)))
; __device__ __forceinline__ unsigned cvt_pk_bf16(float lo, float hi) { unsigned r; asm volatile("v_cvt_pk_bf16_f32 %0, %1, %2" : "=v"(r) : "v"(lo), "v"(hi)); return r; }
;     __device__ __forceinline__ void operator()(const f32x4 (&acc)[2][2][4][2], const Unit& u, int wr, int wc, int fr, int fq) const {
;     ...
;                 for (int bj = 0; bj < 2; ++bj) {
;                     const size_t off = (size_t)row * 2048 + u.pn * BM + wc * 64 + bj * 32 + 8 * p;
;                     f32x4 b0, b1;
;                     if (BASE_F32) { b0 = *(const f32x4*)((const float*)base + off); b1 = *(const f32x4*)((const float*)base + off + 4); }
;                     else { const u32x4 bb = *(const u32x4*)((const bf16_t*)base + off);
;                         b0 = (f32x4){__uint_as_float(bb.x << 16), __uint_as_float(bb.x & 0xffff0000u), __uint_as_float(bb.y << 16), __uint_as_float(bb.y & 0xffff0000u)};
;                         b1 = (f32x4){__uint_as_float(bb.z << 16), __uint_as_float(bb.z & 0xffff0000u), __uint_as_float(bb.w << 16), __uint_as_float(bb.w & 0xffff0000u)}; }
; #pragma unroll
;                     for (int n = 0; n < 2; ++n) *(PG8_LAS f32x4*)(stg + fr * STG_ROW + n * 64 + fq * 16) = acc[ai][bj][m][n];
;                     const f32x4 v0 = *(const PG8_LAS f32x4*)(stg + r * STG_ROW + p * 32) + b0, v1 = *(const PG8_LAS f32x4*)(stg + r * STG_ROW + p * 32 + 16) + b1;
;                     q += ((v0[0] * v0[0] + v0[1] * v0[1]) + (v0[2] * v0[2] + v0[3] * v0[3])) + ((v1[0] * v1[0] + v1[1] * v1[1]) + (v1[2] * v1[2] + v1[3] * v1[3]));
;                     u32x4 w; w.x = cvt_pk_bf16(v0[0], v0[1]); w.y = cvt_pk_bf16(v0[2], v0[3]); w.z = cvt_pk_bf16(v1[0], v1[1]); w.w = cvt_pk_bf16(v1[2], v1[3]);
;                     *(u32x4*)(out + off) = w;
;                 }
;                 q += __shfl_xor(q, 1); q += __shfl_xor(q, 2);
;                 if (p == 0) atomicAdd(ssn + row, (u64)(q * SS_SCALE));
	v_lshlrev_b32_e32 v236, 16, v192
	v_and_b32_e32 v237, 0xffff0000, v192
	v_lshlrev_b32_e32 v238, 16, v193
	v_and_b32_e32 v239, 0xffff0000, v193
	v_lshlrev_b32_e32 v240, 16, v194
	v_and_b32_e32 v241, 0xffff0000, v194
	v_lshlrev_b32_e32 v242, 16, v195
	v_and_b32_e32 v243, 0xffff0000, v195
	v_pk_add_f32 v[56:57], v[56:57], v[236:237]
	v_pk_add_f32 v[58:59], v[58:59], v[238:239]
	v_pk_add_f32 v[60:61], v[60:61], v[240:241]
	v_pk_add_f32 v[62:63], v[62:63], v[242:243]
	v_mul_f32_e32 v236, v57, v57
	v_mul_f32_e32 v237, v59, v59
	v_mul_f32_e32 v238, v61, v61
	v_mul_f32_e32 v239, v63, v63
	v_fmac_f32_e32 v236, v56, v56
	v_fmac_f32_e32 v237, v58, v58
	v_fmac_f32_e32 v238, v60, v60
	v_fmac_f32_e32 v239, v62, v62
	v_cvt_pk_bf16_f32 v56, v56, v57
	v_cvt_pk_bf16_f32 v57, v58, v59
	v_cvt_pk_bf16_f32 v58, v60, v61
	v_cvt_pk_bf16_f32 v59, v62, v63
	v_add_f32_e32 v236, v236, v237
	v_add_f32_e32 v237, v238, v239
	v_add_f32_e32 v60, v236, v237
	v_add_u32_e32 v146, 0x80000, v159
	global_store_dwordx4 v146, v[56:59], s[28:29]
	ds_write_b128 v156, v[44:47]
	ds_write_b128 v156, v[40:43] offset:64
	ds_read_b128 v[40:43], v157
	ds_read_b128 v[44:47], v157 offset:16
	s_waitcnt vmcnt(15) lgkmcnt(4)
	v_lshlrev_b32_e32 v236, 16, v196
	v_and_b32_e32 v237, 0xffff0000, v196
	v_lshlrev_b32_e32 v238, 16, v197
	v_and_b32_e32 v239, 0xffff0000, v197
	v_lshlrev_b32_e32 v240, 16, v198
	v_and_b32_e32 v241, 0xffff0000, v198
	v_lshlrev_b32_e32 v242, 16, v199
	v_and_b32_e32 v243, 0xffff0000, v199
	v_pk_add_f32 v[48:49], v[48:49], v[236:237]
	v_pk_add_f32 v[50:51], v[50:51], v[238:239]
	v_pk_add_f32 v[52:53], v[52:53], v[240:241]
	v_pk_add_f32 v[54:55], v[54:55], v[242:243]
	v_mul_f32_e32 v236, v49, v49
	v_mul_f32_e32 v237, v51, v51
	v_mul_f32_e32 v238, v53, v53
	v_mul_f32_e32 v239, v55, v55
	v_fmac_f32_e32 v236, v48, v48
	v_fmac_f32_e32 v237, v50, v50
	v_fmac_f32_e32 v238, v52, v52
	v_fmac_f32_e32 v239, v54, v54
	v_cvt_pk_bf16_f32 v48, v48, v49
	v_cvt_pk_bf16_f32 v49, v50, v51
	v_cvt_pk_bf16_f32 v50, v52, v53
	v_cvt_pk_bf16_f32 v51, v54, v55
	v_add_f32_e32 v236, v236, v237
	v_add_f32_e32 v237, v238, v239
	v_add_f32_e32 v52, v236, v237
	global_store_dwordx4 v146, v[48:51], s[28:29] offset:64
	v_add_f32_e32 v53, v60, v52
	s_nop 1
	v_add_f32_dpp v54, v53, v53 quad_perm:[1,0,3,2] row_mask:0xf bank_mask:0xf
	s_nop 1
	v_add_f32_dpp v55, v54, v54 quad_perm:[2,3,0,1] row_mask:0xf bank_mask:0xf
	v_mul_f32_e32 v62, 0x49800000, v55
	v_trunc_f32_e32 v62, v62
	v_mul_f32_e32 v63, 0x2f800000, v62
	v_floor_f32_e32 v63, v63
	v_fmac_f32_e32 v62, 0xcf800000, v63
	v_cvt_u32_f32_e32 v62, v62
	v_cvt_u32_f32_e32 v63, v63
	ds_write_b128 v156, v[36:39]
	ds_write_b128 v156, v[32:35] offset:64
	ds_read_b128 v[32:35], v157
	ds_read_b128 v[36:39], v157 offset:16
	s_waitcnt vmcnt(15) lgkmcnt(4)
	v_lshlrev_b32_e32 v236, 16, v200
	v_and_b32_e32 v237, 0xffff0000, v200
	v_lshlrev_b32_e32 v238, 16, v201
	v_and_b32_e32 v239, 0xffff0000, v201
	v_lshlrev_b32_e32 v240, 16, v202
	v_and_b32_e32 v241, 0xffff0000, v202
	v_lshlrev_b32_e32 v242, 16, v203
	v_and_b32_e32 v243, 0xffff0000, v203
	v_pk_add_f32 v[40:41], v[40:41], v[236:237]
	v_pk_add_f32 v[42:43], v[42:43], v[238:239]
	v_pk_add_f32 v[44:45], v[44:45], v[240:241]
	v_pk_add_f32 v[46:47], v[46:47], v[242:243]
	v_mul_f32_e32 v236, v41, v41
	v_mul_f32_e32 v237, v43, v43
	v_mul_f32_e32 v238, v45, v45
	v_mul_f32_e32 v239, v47, v47
	v_fmac_f32_e32 v236, v40, v40
	v_fmac_f32_e32 v237, v42, v42
	v_fmac_f32_e32 v238, v44, v44
	v_fmac_f32_e32 v239, v46, v46
	v_cvt_pk_bf16_f32 v40, v40, v41
	v_cvt_pk_bf16_f32 v41, v42, v43
	v_cvt_pk_bf16_f32 v42, v44, v45
	v_cvt_pk_bf16_f32 v43, v46, v47
	v_add_f32_e32 v236, v236, v237
	v_add_f32_e32 v237, v238, v239
	v_add_f32_e32 v44, v236, v237
	v_add_u32_e32 v147, 0x90000, v159
	global_store_dwordx4 v147, v[40:43], s[28:29]
	ds_write_b128 v156, v[28:31]
	ds_write_b128 v156, v[24:27] offset:64
	ds_read_b128 v[24:27], v157
	ds_read_b128 v[28:31], v157 offset:16
	s_waitcnt vmcnt(15) lgkmcnt(4)
	v_lshlrev_b32_e32 v236, 16, v204
	v_and_b32_e32 v237, 0xffff0000, v204
	v_lshlrev_b32_e32 v238, 16, v205
	v_and_b32_e32 v239, 0xffff0000, v205
	v_lshlrev_b32_e32 v240, 16, v206
	v_and_b32_e32 v241, 0xffff0000, v206
	v_lshlrev_b32_e32 v242, 16, v207
	v_and_b32_e32 v243, 0xffff0000, v207
	v_pk_add_f32 v[32:33], v[32:33], v[236:237]
	v_pk_add_f32 v[34:35], v[34:35], v[238:239]
	v_pk_add_f32 v[36:37], v[36:37], v[240:241]
	v_pk_add_f32 v[38:39], v[38:39], v[242:243]
	v_mul_f32_e32 v236, v33, v33
	v_mul_f32_e32 v237, v35, v35
	v_mul_f32_e32 v238, v37, v37
	v_mul_f32_e32 v239, v39, v39
	v_fmac_f32_e32 v236, v32, v32
	v_fmac_f32_e32 v237, v34, v34
	v_fmac_f32_e32 v238, v36, v36
	v_fmac_f32_e32 v239, v38, v38
	v_cvt_pk_bf16_f32 v32, v32, v33
	v_cvt_pk_bf16_f32 v33, v34, v35
	v_cvt_pk_bf16_f32 v34, v36, v37
	v_cvt_pk_bf16_f32 v35, v38, v39
	v_add_f32_e32 v236, v236, v237
	v_add_f32_e32 v237, v238, v239
	v_add_f32_e32 v36, v236, v237
	global_store_dwordx4 v147, v[32:35], s[28:29] offset:64
	v_add_f32_e32 v37, v44, v36
	s_nop 1
	v_add_f32_dpp v38, v37, v37 quad_perm:[1,0,3,2] row_mask:0xf bank_mask:0xf
	s_nop 1
	v_add_f32_dpp v39, v38, v38 quad_perm:[2,3,0,1] row_mask:0xf bank_mask:0xf
	v_mul_f32_e32 v46, 0x49800000, v39
	v_trunc_f32_e32 v46, v46
	v_mul_f32_e32 v47, 0x2f800000, v46
	v_floor_f32_e32 v47, v47
	v_fmac_f32_e32 v46, 0xcf800000, v47
	v_cvt_u32_f32_e32 v46, v46
	v_cvt_u32_f32_e32 v47, v47
	ds_write_b128 v156, v[20:23]
	ds_write_b128 v156, v[16:19] offset:64
	ds_read_b128 v[16:19], v157
	ds_read_b128 v[20:23], v157 offset:16
	s_waitcnt vmcnt(15) lgkmcnt(4)
; #define PG8_LAS __attribute__((address_space(3)))
; __device__ __forceinline__ unsigned cvt_pk_bf16(float lo, float hi) { unsigned r; asm volatile("v_cvt_pk_bf16_f32 %0, %1, %2" : "=v"(r) : "v"(lo), "v"(hi)); return r; }
;     __device__ __forceinline__ void operator()(const f32x4 (&acc)[2][2][4][2], const Unit& u, int wr, int wc, int fr, int fq) const {
;     ...
;                 for (int bj = 0; bj < 2; ++bj) {
;                     const size_t off = (size_t)row * 2048 + u.pn * BM + wc * 64 + bj * 32 + 8 * p;
;                     f32x4 b0, b1;
;                     if (BASE_F32) { b0 = *(const f32x4*)((const float*)base + off); b1 = *(const f32x4*)((const float*)base + off + 4); }
;                     else { const u32x4 bb = *(const u32x4*)((const bf16_t*)base + off);
;                         b0 = (f32x4){__uint_as_float(bb.x << 16), __uint_as_float(bb.x & 0xffff0000u), __uint_as_float(bb.y << 16), __uint_as_float(bb.y & 0xffff0000u)};
;                         b1 = (f32x4){__uint_as_float(bb.z << 16), __uint_as_float(bb.z & 0xffff0000u), __uint_as_float(bb.w << 16), __uint_as_float(bb.w & 0xffff0000u)}; }
; #pragma unroll
;                     for (int n = 0; n < 2; ++n) *(PG8_LAS f32x4*)(stg + fr * STG_ROW + n * 64 + fq * 16) = acc[ai][bj][m][n];
;                     const f32x4 v0 = *(const PG8_LAS f32x4*)(stg + r * STG_ROW + p * 32) + b0, v1 = *(const PG8_LAS f32x4*)(stg + r * STG_ROW + p * 32 + 16) + b1;
;                     q += ((v0[0] * v0[0] + v0[1] * v0[1]) + (v0[2] * v0[2] + v0[3] * v0[3])) + ((v1[0] * v1[0] + v1[1] * v1[1]) + (v1[2] * v1[2] + v1[3] * v1[3]));
;                     u32x4 w; w.x = cvt_pk_bf16(v0[0], v0[1]); w.y = cvt_pk_bf16(v0[2], v0[3]); w.z = cvt_pk_bf16(v1[0], v1[1]); w.w = cvt_pk_bf16(v1[2], v1[3]);
;                     *(u32x4*)(out + off) = w;
;                 }
;                 q += __shfl_xor(q, 1); q += __shfl_xor(q, 2);
;                 if (p == 0) atomicAdd(ssn + row, (u64)(q * SS_SCALE));
	v_lshlrev_b32_e32 v236, 16, v212
	v_and_b32_e32 v237, 0xffff0000, v212
	v_lshlrev_b32_e32 v238, 16, v213
	v_and_b32_e32 v239, 0xffff0000, v213
	v_lshlrev_b32_e32 v240, 16, v214
	v_and_b32_e32 v241, 0xffff0000, v214
	v_lshlrev_b32_e32 v242, 16, v215
	v_and_b32_e32 v243, 0xffff0000, v215
	v_pk_add_f32 v[24:25], v[24:25], v[236:237]
	v_pk_add_f32 v[26:27], v[26:27], v[238:239]
	v_pk_add_f32 v[28:29], v[28:29], v[240:241]
	v_pk_add_f32 v[30:31], v[30:31], v[242:243]
	v_mul_f32_e32 v236, v25, v25
	v_mul_f32_e32 v237, v27, v27
	v_mul_f32_e32 v238, v29, v29
	v_mul_f32_e32 v239, v31, v31
	v_fmac_f32_e32 v236, v24, v24
	v_fmac_f32_e32 v237, v26, v26
	v_fmac_f32_e32 v238, v28, v28
	v_fmac_f32_e32 v239, v30, v30
	v_cvt_pk_bf16_f32 v24, v24, v25
	v_cvt_pk_bf16_f32 v25, v26, v27
	v_cvt_pk_bf16_f32 v26, v28, v29
	v_cvt_pk_bf16_f32 v27, v30, v31
	v_add_f32_e32 v236, v236, v237
	v_add_f32_e32 v237, v238, v239
	v_add_f32_e32 v28, v236, v237
	v_add_u32_e32 v146, 0xa0000, v159
	global_store_dwordx4 v146, v[24:27], s[28:29]
	ds_write_b128 v156, v[12:15]
	ds_write_b128 v156, v[8:11] offset:64
	ds_read_b128 v[8:11], v157
	ds_read_b128 v[12:15], v157 offset:16
	s_waitcnt vmcnt(15) lgkmcnt(4)
	v_lshlrev_b32_e32 v236, 16, v216
	v_and_b32_e32 v237, 0xffff0000, v216
	v_lshlrev_b32_e32 v238, 16, v217
	v_and_b32_e32 v239, 0xffff0000, v217
	v_lshlrev_b32_e32 v240, 16, v218
	v_and_b32_e32 v241, 0xffff0000, v218
	v_lshlrev_b32_e32 v242, 16, v219
	v_and_b32_e32 v243, 0xffff0000, v219
	v_pk_add_f32 v[16:17], v[16:17], v[236:237]
	v_pk_add_f32 v[18:19], v[18:19], v[238:239]
	v_pk_add_f32 v[20:21], v[20:21], v[240:241]
	v_pk_add_f32 v[22:23], v[22:23], v[242:243]
	v_mul_f32_e32 v236, v17, v17
	v_mul_f32_e32 v237, v19, v19
	v_mul_f32_e32 v238, v21, v21
	v_mul_f32_e32 v239, v23, v23
	v_fmac_f32_e32 v236, v16, v16
	v_fmac_f32_e32 v237, v18, v18
	v_fmac_f32_e32 v238, v20, v20
	v_fmac_f32_e32 v239, v22, v22
	v_cvt_pk_bf16_f32 v16, v16, v17
	v_cvt_pk_bf16_f32 v17, v18, v19
	v_cvt_pk_bf16_f32 v18, v20, v21
	v_cvt_pk_bf16_f32 v19, v22, v23
	v_add_f32_e32 v236, v236, v237
	v_add_f32_e32 v237, v238, v239
	v_add_f32_e32 v20, v236, v237
	global_store_dwordx4 v146, v[16:19], s[28:29] offset:64
	v_add_f32_e32 v21, v28, v20
	s_nop 1
	v_add_f32_dpp v22, v21, v21 quad_perm:[1,0,3,2] row_mask:0xf bank_mask:0xf
	s_nop 1
	v_add_f32_dpp v23, v22, v22 quad_perm:[2,3,0,1] row_mask:0xf bank_mask:0xf
	v_mul_f32_e32 v30, 0x49800000, v23
	v_trunc_f32_e32 v30, v30
	v_mul_f32_e32 v31, 0x2f800000, v30
	v_floor_f32_e32 v31, v31
	v_fmac_f32_e32 v30, 0xcf800000, v31
	v_cvt_u32_f32_e32 v30, v30
	v_cvt_u32_f32_e32 v31, v31
	ds_write_b128 v156, v[4:7]
	ds_write_b128 v156, v[0:3] offset:64
	ds_read_b128 v[0:3], v157
	ds_read_b128 v[4:7], v157 offset:16
	s_waitcnt vmcnt(15) lgkmcnt(4)
	v_lshlrev_b32_e32 v236, 16, v220
	v_and_b32_e32 v237, 0xffff0000, v220
	v_lshlrev_b32_e32 v238, 16, v221
	v_and_b32_e32 v239, 0xffff0000, v221
	v_lshlrev_b32_e32 v240, 16, v222
	v_and_b32_e32 v241, 0xffff0000, v222
	v_lshlrev_b32_e32 v242, 16, v223
	v_and_b32_e32 v243, 0xffff0000, v223
	v_pk_add_f32 v[8:9], v[8:9], v[236:237]
	v_pk_add_f32 v[10:11], v[10:11], v[238:239]
	v_pk_add_f32 v[12:13], v[12:13], v[240:241]
	v_pk_add_f32 v[14:15], v[14:15], v[242:243]
	v_mul_f32_e32 v236, v9, v9
	v_mul_f32_e32 v237, v11, v11
	v_mul_f32_e32 v238, v13, v13
	v_mul_f32_e32 v239, v15, v15
	v_fmac_f32_e32 v236, v8, v8
	v_fmac_f32_e32 v237, v10, v10
	v_fmac_f32_e32 v238, v12, v12
	v_fmac_f32_e32 v239, v14, v14
	v_cvt_pk_bf16_f32 v8, v8, v9
	v_cvt_pk_bf16_f32 v9, v10, v11
	v_cvt_pk_bf16_f32 v10, v12, v13
	v_cvt_pk_bf16_f32 v11, v14, v15
	v_add_f32_e32 v236, v236, v237
	v_add_f32_e32 v237, v238, v239
	v_add_f32_e32 v12, v236, v237
	v_add_u32_e32 v147, 0xb0000, v159
	global_store_dwordx4 v147, v[8:11], s[28:29]
	s_waitcnt vmcnt(15) lgkmcnt(0)
	v_lshlrev_b32_e32 v236, 16, v224
	v_and_b32_e32 v237, 0xffff0000, v224
	v_lshlrev_b32_e32 v238, 16, v225
	v_and_b32_e32 v239, 0xffff0000, v225
	v_lshlrev_b32_e32 v240, 16, v226
	v_and_b32_e32 v241, 0xffff0000, v226
	v_lshlrev_b32_e32 v242, 16, v227
	v_and_b32_e32 v243, 0xffff0000, v227
	v_pk_add_f32 v[0:1], v[0:1], v[236:237]
	v_pk_add_f32 v[2:3], v[2:3], v[238:239]
	v_pk_add_f32 v[4:5], v[4:5], v[240:241]
	v_pk_add_f32 v[6:7], v[6:7], v[242:243]
	v_mul_f32_e32 v236, v1, v1
	v_mul_f32_e32 v237, v3, v3
	v_mul_f32_e32 v238, v5, v5
	v_mul_f32_e32 v239, v7, v7
	v_fmac_f32_e32 v236, v0, v0
	v_fmac_f32_e32 v237, v2, v2
	v_fmac_f32_e32 v238, v4, v4
	v_fmac_f32_e32 v239, v6, v6
	v_cvt_pk_bf16_f32 v0, v0, v1
	v_cvt_pk_bf16_f32 v1, v2, v3
	v_cvt_pk_bf16_f32 v2, v4, v5
	v_cvt_pk_bf16_f32 v3, v6, v7
	v_add_f32_e32 v236, v236, v237
	v_add_f32_e32 v237, v238, v239
	v_add_f32_e32 v4, v236, v237
	global_store_dwordx4 v147, v[0:3], s[28:29] offset:64
	v_add_f32_e32 v5, v12, v4
	s_nop 1
	v_add_f32_dpp v6, v5, v5 quad_perm:[1,0,3,2] row_mask:0xf bank_mask:0xf
	s_nop 1
	v_add_f32_dpp v7, v6, v6 quad_perm:[2,3,0,1] row_mask:0xf bank_mask:0xf
	v_mul_f32_e32 v14, 0x49800000, v7
	v_trunc_f32_e32 v14, v14
	v_mul_f32_e32 v15, 0x2f800000, v14
	v_floor_f32_e32 v15, v15
	v_fmac_f32_e32 v14, 0xcf800000, v15
	v_cvt_u32_f32_e32 v14, v14
	v_cvt_u32_f32_e32 v15, v15
	v_and_b32_e32 v236, 3, v252
	v_lshl_add_u32 v237, v236, 7, v208
	v_cmp_eq_u32_e64 s[100:101], 1, v236
	v_cndmask_b32_e64 v126, v126, v110, s[100:101]
	v_cndmask_b32_e64 v127, v127, v111, s[100:101]
	v_cmp_eq_u32_e64 s[100:101], 2, v236
	v_cndmask_b32_e64 v126, v126, v94, s[100:101]
	v_cndmask_b32_e64 v127, v127, v95, s[100:101]
	v_cmp_eq_u32_e64 s[100:101], 3, v236
	v_cndmask_b32_e64 v126, v126, v78, s[100:101]
	v_cndmask_b32_e64 v127, v127, v79, s[100:101]
	global_atomic_add_x2 v237, v[126:127], s[12:13]
	v_cmp_eq_u32_e64 s[100:101], 1, v236
	v_cndmask_b32_e64 v62, v62, v46, s[100:101]
	v_cndmask_b32_e64 v63, v63, v47, s[100:101]
	v_cmp_eq_u32_e64 s[100:101], 2, v236
	v_cndmask_b32_e64 v62, v62, v30, s[100:101]
	v_cndmask_b32_e64 v63, v63, v31, s[100:101]
	v_cmp_eq_u32_e64 s[100:101], 3, v236
	v_cndmask_b32_e64 v62, v62, v14, s[100:101]
	v_cndmask_b32_e64 v63, v63, v15, s[100:101]
	global_atomic_add_x2 v237, v[62:63], s[12:13] offset:1024
	s_and_b64 vcc, exec, s[8:9]
	s_mov_b64 s[8:9], -1
	s_cbranch_vccnz .LBB0_939
	s_andn2_b64 vcc, exec, s[36:37]
	s_cbranch_vccnz .LBB0_938
	s_mov_b32 s98, 1
	s_branch .LBB0_938
